# v18 + dpost gate-matmul loop rewritten: weights prefetched one iteration ahead, su LDS reads double-buffered (bit-identical)
# speedup vs baseline: 1.0796x; 1.0163x over previous
.LBB0_634:
	s_or_b64 exec, exec, s[4:5]
	s_waitcnt vmcnt(0)
	v_lshlrev_b32_e32 v4, 16, v9
	v_pk_add_f32 v[6:7], v[6:7], v[4:5] op_sel_hi:[1,0] neg_lo:[0,1] neg_hi:[0,1]
	v_lshl_add_u32 v1, v8, 2, v1
	v_pk_mul_f32 v[2:3], v[2:3], v[6:7]
	s_ashr_i32 s13, s12, 31
	v_add_f32_e32 v2, v2, v4
	v_add_f32_e32 v2, v2, v3
	v_mul_f32_e32 v2, 0xbfb8aa3b, v2
	v_exp_f32_e32 v2, v2
	s_movk_i32 s37, 0x1000
	v_add_f32_e32 v2, 1.0, v2
	v_div_scale_f32 v3, s[4:5], v2, v2, 1.0
	v_rcp_f32_e32 v4, v3
	v_div_scale_f32 v5, vcc, 1.0, v2, 1.0
	s_mul_i32 s4, s12, 0x1a80
	v_fma_f32 v6, -v3, v4, 1.0
	v_fmac_f32_e32 v4, v6, v4
	v_mul_f32_e32 v6, v5, v4
	v_fma_f32 v7, -v3, v6, v5
	v_fmac_f32_e32 v6, v7, v4
	v_fma_f32 v3, -v3, v6, v5
	v_div_fmas_f32 v3, v3, v4, v6
	v_div_fixup_f32 v2, v3, v2, 1.0
	ds_write_b32 v1, v2
	v_ashrrev_i32_e32 v1, 31, v0
	s_mul_hi_i32 s5, s12, 0x1a80
	s_add_u32 s4, s78, s4
	s_addc_u32 s5, s79, s5
	v_lshlrev_b64 v[2:3], 1, v[0:1]
	s_lshl_b64 s[14:15], s[12:13], 8
	v_lshl_add_u64 v[6:7], s[4:5], 0, v[2:3]
	s_or_b32 s4, s12, 1
	v_lshl_add_u64 v[4:5], s[14:15], 0, v[0:1]
	v_add_co_u32_e32 v6, vcc, s37, v6
	s_ashr_i32 s5, s4, 31
	s_mul_i32 s14, s4, 0x1a80
	v_addc_co_u32_e32 v7, vcc, 0, v7, vcc
	v_lshlrev_b64 v[4:5], 1, v[4:5]
	s_mul_hi_i32 s13, s4, 0x1a80
	s_add_u32 s14, s78, s14
	s_waitcnt lgkmcnt(0)
	s_barrier
	global_load_ushort v34, v[6:7], off offset:512 nt
	global_load_ushort v35, v[6:7], off offset:1024 nt
	v_lshl_add_u64 v[6:7], s[80:81], 0, v[4:5]
	v_lshl_add_u64 v[8:9], s[94:95], 0, v[4:5]
	v_lshl_add_u64 v[4:5], s[96:97], 0, v[4:5]
	s_addc_u32 s15, s79, s13
	s_lshl_b64 s[4:5], s[4:5], 8
	global_load_ushort v36, v[6:7], off nt
	global_load_ushort v45, v[8:9], off nt
	global_load_ushort v64, v[4:5], off nt
	v_lshl_add_u64 v[4:5], s[4:5], 0, v[0:1]
	v_lshl_add_u64 v[6:7], s[14:15], 0, v[2:3]
	s_or_b32 s4, s12, 2
	v_add_co_u32_e32 v6, vcc, s37, v6
	s_ashr_i32 s5, s4, 31
	s_mul_i32 s14, s4, 0x1a80
	v_addc_co_u32_e32 v7, vcc, 0, v7, vcc
	v_lshlrev_b64 v[4:5], 1, v[4:5]
	s_mul_hi_i32 s13, s4, 0x1a80
	s_add_u32 s14, s78, s14
	global_load_ushort v65, v[6:7], off offset:512 nt
	global_load_ushort v66, v[6:7], off offset:1024 nt
	v_lshl_add_u64 v[6:7], s[80:81], 0, v[4:5]
	v_lshl_add_u64 v[8:9], s[94:95], 0, v[4:5]
	v_lshl_add_u64 v[4:5], s[96:97], 0, v[4:5]
	s_addc_u32 s15, s79, s13
	s_lshl_b64 s[4:5], s[4:5], 8
	global_load_ushort v67, v[6:7], off nt
	global_load_ushort v68, v[8:9], off nt
	global_load_ushort v69, v[4:5], off nt
	v_lshl_add_u64 v[4:5], s[4:5], 0, v[0:1]
	v_lshl_add_u64 v[6:7], s[14:15], 0, v[2:3]
	s_or_b32 s4, s12, 3
	v_add_co_u32_e32 v6, vcc, s37, v6
	s_ashr_i32 s5, s4, 31
	s_mul_i32 s14, s4, 0x1a80
	v_addc_co_u32_e32 v7, vcc, 0, v7, vcc
	v_lshlrev_b64 v[4:5], 1, v[4:5]
	s_mul_hi_i32 s13, s4, 0x1a80
	s_add_u32 s14, s78, s14
	global_load_ushort v71, v[6:7], off offset:512 nt
	global_load_ushort v72, v[6:7], off offset:1024 nt
	v_lshl_add_u64 v[6:7], s[80:81], 0, v[4:5]
	v_lshl_add_u64 v[8:9], s[94:95], 0, v[4:5]
	v_lshl_add_u64 v[4:5], s[96:97], 0, v[4:5]
	s_addc_u32 s15, s79, s13
	s_lshl_b64 s[4:5], s[4:5], 8
	global_load_ushort v75, v[6:7], off nt
	global_load_ushort v76, v[8:9], off nt
	global_load_ushort v77, v[4:5], off nt
	v_lshl_add_u64 v[4:5], s[4:5], 0, v[0:1]
	v_lshl_add_u64 v[6:7], s[14:15], 0, v[2:3]
	s_or_b32 s4, s12, 4
	v_add_co_u32_e32 v6, vcc, s37, v6
	s_ashr_i32 s5, s4, 31
	s_mul_i32 s14, s4, 0x1a80
	v_addc_co_u32_e32 v7, vcc, 0, v7, vcc
	v_lshlrev_b64 v[4:5], 1, v[4:5]
	s_mul_hi_i32 s13, s4, 0x1a80
	s_add_u32 s14, s78, s14
	global_load_ushort v79, v[6:7], off offset:512 nt
	global_load_ushort v80, v[6:7], off offset:1024 nt
	v_lshl_add_u64 v[6:7], s[80:81], 0, v[4:5]
	v_lshl_add_u64 v[8:9], s[94:95], 0, v[4:5]
	v_lshl_add_u64 v[4:5], s[96:97], 0, v[4:5]
	s_addc_u32 s15, s79, s13
	s_lshl_b64 s[4:5], s[4:5], 8
	global_load_ushort v81, v[6:7], off nt
	global_load_ushort v82, v[8:9], off nt
	global_load_ushort v83, v[4:5], off nt
	v_lshl_add_u64 v[4:5], s[4:5], 0, v[0:1]
	v_lshl_add_u64 v[6:7], s[14:15], 0, v[2:3]
	s_or_b32 s4, s12, 5
	v_add_co_u32_e32 v6, vcc, s37, v6
	s_ashr_i32 s5, s4, 31
	s_mul_i32 s14, s4, 0x1a80
	v_addc_co_u32_e32 v7, vcc, 0, v7, vcc
	v_lshlrev_b64 v[4:5], 1, v[4:5]
	s_mul_hi_i32 s13, s4, 0x1a80
	s_add_u32 s14, s78, s14
	global_load_ushort v85, v[6:7], off offset:512 nt
	global_load_ushort v86, v[6:7], off offset:1024 nt
	v_lshl_add_u64 v[6:7], s[80:81], 0, v[4:5]
	v_lshl_add_u64 v[8:9], s[94:95], 0, v[4:5]
	v_lshl_add_u64 v[4:5], s[96:97], 0, v[4:5]
	s_addc_u32 s15, s79, s13
	s_lshl_b64 s[4:5], s[4:5], 8
	global_load_ushort v87, v[6:7], off nt
	global_load_ushort v88, v[8:9], off nt
	global_load_ushort v84, v[4:5], off nt
	v_lshl_add_u64 v[4:5], s[4:5], 0, v[0:1]
	v_lshl_add_u64 v[6:7], s[14:15], 0, v[2:3]
	s_or_b32 s4, s12, 6
	v_add_co_u32_e32 v6, vcc, s37, v6
	s_ashr_i32 s5, s4, 31
	s_mul_i32 s14, s4, 0x1a80
	v_addc_co_u32_e32 v7, vcc, 0, v7, vcc
	v_lshlrev_b64 v[4:5], 1, v[4:5]
	s_mul_hi_i32 s13, s4, 0x1a80
	s_add_u32 s14, s78, s14
	global_load_ushort v78, v[6:7], off offset:512 nt
	global_load_ushort v89, v[6:7], off offset:1024 nt
	v_lshl_add_u64 v[6:7], s[80:81], 0, v[4:5]
	v_lshl_add_u64 v[8:9], s[94:95], 0, v[4:5]
	v_lshl_add_u64 v[4:5], s[96:97], 0, v[4:5]
	s_addc_u32 s15, s79, s13
	s_lshl_b64 s[4:5], s[4:5], 8
	global_load_ushort v74, v[6:7], off nt
	global_load_ushort v73, v[8:9], off nt
	global_load_ushort v70, v[4:5], off nt
	v_lshl_add_u64 v[4:5], s[4:5], 0, v[0:1]
	v_lshl_add_u64 v[6:7], s[14:15], 0, v[2:3]
	s_or_b32 s4, s12, 7
	v_add_co_u32_e32 v6, vcc, s37, v6
	s_ashr_i32 s5, s4, 31
	s_mul_i32 s14, s4, 0x1a80
	v_addc_co_u32_e32 v7, vcc, 0, v7, vcc
	v_lshlrev_b64 v[4:5], 1, v[4:5]
	s_mul_hi_i32 s13, s4, 0x1a80
	s_add_u32 s14, s78, s14
	global_load_ushort v61, v[6:7], off offset:512 nt
	global_load_ushort v90, v[6:7], off offset:1024 nt
	v_lshl_add_u64 v[6:7], s[80:81], 0, v[4:5]
	v_lshl_add_u64 v[8:9], s[94:95], 0, v[4:5]
	v_lshl_add_u64 v[4:5], s[96:97], 0, v[4:5]
	s_addc_u32 s15, s79, s13
	s_lshl_b64 s[4:5], s[4:5], 8
	global_load_ushort v63, v[6:7], off nt
	global_load_ushort v62, v[8:9], off nt
	global_load_ushort v60, v[4:5], off nt
	v_lshl_add_u64 v[4:5], s[4:5], 0, v[0:1]
	v_lshl_add_u64 v[6:7], s[14:15], 0, v[2:3]
	s_or_b32 s4, s12, 8
	v_add_co_u32_e32 v6, vcc, s37, v6
	s_ashr_i32 s5, s4, 31
	s_mul_i32 s14, s4, 0x1a80
	v_addc_co_u32_e32 v7, vcc, 0, v7, vcc
	v_lshlrev_b64 v[4:5], 1, v[4:5]
	s_mul_hi_i32 s13, s4, 0x1a80
	s_add_u32 s14, s78, s14
	global_load_ushort v59, v[6:7], off offset:512 nt
	global_load_ushort v91, v[6:7], off offset:1024 nt
	v_lshl_add_u64 v[6:7], s[80:81], 0, v[4:5]
	v_lshl_add_u64 v[8:9], s[94:95], 0, v[4:5]
	v_lshl_add_u64 v[4:5], s[96:97], 0, v[4:5]
	s_addc_u32 s15, s79, s13
	s_lshl_b64 s[4:5], s[4:5], 8
	global_load_ushort v58, v[6:7], off nt
	global_load_ushort v57, v[8:9], off nt
	global_load_ushort v56, v[4:5], off nt
	v_lshl_add_u64 v[4:5], s[4:5], 0, v[0:1]
	v_lshl_add_u64 v[6:7], s[14:15], 0, v[2:3]
	s_or_b32 s4, s12, 9
	v_add_co_u32_e32 v6, vcc, s37, v6
	s_ashr_i32 s5, s4, 31
	s_mul_i32 s14, s4, 0x1a80
	v_addc_co_u32_e32 v7, vcc, 0, v7, vcc
	v_lshlrev_b64 v[4:5], 1, v[4:5]
	s_mul_hi_i32 s13, s4, 0x1a80
	s_add_u32 s14, s78, s14
	global_load_ushort v53, v[6:7], off offset:512 nt
	global_load_ushort v92, v[6:7], off offset:1024 nt
	v_lshl_add_u64 v[6:7], s[80:81], 0, v[4:5]
	v_lshl_add_u64 v[8:9], s[94:95], 0, v[4:5]
	v_lshl_add_u64 v[4:5], s[96:97], 0, v[4:5]
	s_addc_u32 s15, s79, s13
	s_lshl_b64 s[4:5], s[4:5], 8
	global_load_ushort v55, v[6:7], off nt
	global_load_ushort v54, v[8:9], off nt
	global_load_ushort v52, v[4:5], off nt
	v_lshl_add_u64 v[4:5], s[4:5], 0, v[0:1]
	v_lshl_add_u64 v[6:7], s[14:15], 0, v[2:3]
	s_or_b32 s4, s12, 10
	v_add_co_u32_e32 v6, vcc, s37, v6
	s_ashr_i32 s5, s4, 31
	s_mul_i32 s14, s4, 0x1a80
	v_addc_co_u32_e32 v7, vcc, 0, v7, vcc
	v_lshlrev_b64 v[4:5], 1, v[4:5]
	s_mul_hi_i32 s13, s4, 0x1a80
	s_add_u32 s14, s78, s14
	global_load_ushort v51, v[6:7], off offset:512 nt
	global_load_ushort v93, v[6:7], off offset:1024 nt
	v_lshl_add_u64 v[6:7], s[80:81], 0, v[4:5]
	v_lshl_add_u64 v[8:9], s[94:95], 0, v[4:5]
	v_lshl_add_u64 v[4:5], s[96:97], 0, v[4:5]
	s_addc_u32 s15, s79, s13
	s_lshl_b64 s[4:5], s[4:5], 8
	global_load_ushort v50, v[6:7], off nt
	global_load_ushort v49, v[8:9], off nt
	global_load_ushort v48, v[4:5], off nt
	v_lshl_add_u64 v[4:5], s[4:5], 0, v[0:1]
	v_lshl_add_u64 v[6:7], s[14:15], 0, v[2:3]
	s_or_b32 s4, s12, 11
	v_add_co_u32_e32 v6, vcc, s37, v6
	s_ashr_i32 s5, s4, 31
	s_mul_i32 s14, s4, 0x1a80
	v_addc_co_u32_e32 v7, vcc, 0, v7, vcc
	v_lshlrev_b64 v[4:5], 1, v[4:5]
	s_mul_hi_i32 s13, s4, 0x1a80
	s_add_u32 s14, s78, s14
	global_load_ushort v44, v[6:7], off offset:512 nt
	global_load_ushort v94, v[6:7], off offset:1024 nt
	v_lshl_add_u64 v[6:7], s[80:81], 0, v[4:5]
	v_lshl_add_u64 v[8:9], s[94:95], 0, v[4:5]
	v_lshl_add_u64 v[4:5], s[96:97], 0, v[4:5]
	s_addc_u32 s15, s79, s13
	s_lshl_b64 s[4:5], s[4:5], 8
	global_load_ushort v47, v[6:7], off nt
	global_load_ushort v46, v[8:9], off nt
	global_load_ushort v43, v[4:5], off nt
	v_lshl_add_u64 v[4:5], s[4:5], 0, v[0:1]
	v_lshl_add_u64 v[6:7], s[14:15], 0, v[2:3]
	s_or_b32 s4, s12, 12
	v_add_co_u32_e32 v6, vcc, s37, v6
	s_ashr_i32 s5, s4, 31
	s_mul_i32 s14, s4, 0x1a80
	v_addc_co_u32_e32 v7, vcc, 0, v7, vcc
	v_lshlrev_b64 v[4:5], 1, v[4:5]
	s_mul_hi_i32 s13, s4, 0x1a80
	s_add_u32 s14, s78, s14
	global_load_ushort v42, v[6:7], off offset:512 nt
	global_load_ushort v95, v[6:7], off offset:1024 nt
	v_lshl_add_u64 v[6:7], s[80:81], 0, v[4:5]
	v_lshl_add_u64 v[8:9], s[94:95], 0, v[4:5]
	v_lshl_add_u64 v[4:5], s[96:97], 0, v[4:5]
	s_addc_u32 s15, s79, s13
	s_lshl_b64 s[4:5], s[4:5], 8
	global_load_ushort v41, v[6:7], off nt
	global_load_ushort v40, v[8:9], off nt
	global_load_ushort v39, v[4:5], off nt
	v_lshl_add_u64 v[4:5], s[4:5], 0, v[0:1]
	v_lshl_add_u64 v[6:7], s[14:15], 0, v[2:3]
	s_or_b32 s4, s12, 13
	v_add_co_u32_e32 v6, vcc, s37, v6
	s_ashr_i32 s5, s4, 31
	s_mul_i32 s14, s4, 0x1a80
	v_addc_co_u32_e32 v7, vcc, 0, v7, vcc
	v_lshlrev_b64 v[4:5], 1, v[4:5]
	s_mul_hi_i32 s13, s4, 0x1a80
	s_add_u32 s14, s78, s14
	global_load_ushort v33, v[6:7], off offset:512 nt
	global_load_ushort v96, v[6:7], off offset:1024 nt
	v_lshl_add_u64 v[6:7], s[80:81], 0, v[4:5]
	v_lshl_add_u64 v[8:9], s[94:95], 0, v[4:5]
	v_lshl_add_u64 v[4:5], s[96:97], 0, v[4:5]
	s_addc_u32 s15, s79, s13
	s_lshl_b64 s[4:5], s[4:5], 8
	global_load_ushort v38, v[6:7], off nt
	global_load_ushort v37, v[8:9], off nt
	global_load_ushort v32, v[4:5], off nt
	v_lshl_add_u64 v[4:5], s[4:5], 0, v[0:1]
	v_lshl_add_u64 v[6:7], s[14:15], 0, v[2:3]
	s_or_b32 s4, s12, 14
	v_add_co_u32_e32 v6, vcc, s37, v6
	s_ashr_i32 s5, s4, 31
	s_mul_i32 s14, s4, 0x1a80
	v_addc_co_u32_e32 v7, vcc, 0, v7, vcc
	v_lshlrev_b64 v[4:5], 1, v[4:5]
	s_mul_hi_i32 s13, s4, 0x1a80
	s_add_u32 s14, s78, s14
	global_load_ushort v31, v[6:7], off offset:512 nt
	global_load_ushort v97, v[6:7], off offset:1024 nt
	v_lshl_add_u64 v[6:7], s[80:81], 0, v[4:5]
	v_lshl_add_u64 v[8:9], s[94:95], 0, v[4:5]
	v_lshl_add_u64 v[4:5], s[96:97], 0, v[4:5]
	s_addc_u32 s15, s79, s13
	s_lshl_b64 s[4:5], s[4:5], 8
	global_load_ushort v30, v[6:7], off nt
	global_load_ushort v29, v[8:9], off nt
	global_load_ushort v28, v[4:5], off nt
	v_lshl_add_u64 v[4:5], s[4:5], 0, v[0:1]
	s_or_b32 s4, s12, 15
	v_lshl_add_u64 v[6:7], s[14:15], 0, v[2:3]
	s_ashr_i32 s5, s4, 31
	s_mul_i32 s14, s4, 0x1a80
	s_mul_hi_i32 s13, s4, 0x1a80
	s_add_u32 s14, s78, s14
	v_add_co_u32_e32 v6, vcc, s37, v6
	s_addc_u32 s15, s79, s13
	s_nop 0
	v_addc_co_u32_e32 v7, vcc, 0, v7, vcc
	v_lshlrev_b64 v[4:5], 1, v[4:5]
	v_lshl_add_u64 v[2:3], s[14:15], 0, v[2:3]
	global_load_ushort v25, v[6:7], off offset:512 nt
	global_load_ushort v98, v[6:7], off offset:1024 nt
	v_lshl_add_u64 v[6:7], s[80:81], 0, v[4:5]
	v_lshl_add_u64 v[8:9], s[94:95], 0, v[4:5]
	v_lshl_add_u64 v[4:5], s[96:97], 0, v[4:5]
	s_lshl_b64 s[4:5], s[4:5], 8
	v_add_co_u32_e32 v2, vcc, s37, v2
	global_load_ushort v27, v[6:7], off nt
	global_load_ushort v26, v[8:9], off nt
	global_load_ushort v24, v[4:5], off nt
	v_lshl_add_u64 v[4:5], s[4:5], 0, v[0:1]
	v_addc_co_u32_e32 v3, vcc, 0, v3, vcc
	global_load_ushort v23, v[2:3], off offset:512 nt
	global_load_ushort v99, v[2:3], off offset:1024 nt
	v_lshlrev_b64 v[2:3], 1, v[4:5]
	v_lshl_add_u64 v[4:5], s[80:81], 0, v[2:3]
	v_lshl_add_u64 v[6:7], s[94:95], 0, v[2:3]
	v_lshl_add_u64 v[2:3], s[96:97], 0, v[2:3]
	global_load_ushort v22, v[4:5], off nt
	global_load_ushort v21, v[6:7], off nt
	global_load_ushort v100, v[2:3], off nt
	v_mov_b32_e32 v2, 0
	s_mov_b32 s4, 0
	v_lshl_add_u64 v[14:15], v[0:1], 2, s[10:11]
	v_mov_b32_e32 v3, v2
	v_mov_b32_e32 v18, v2
	v_mov_b32_e32 v19, v2
	v_mov_b32_e32 v16, v2
	v_mov_b32_e32 v17, v2
	v_mov_b32_e32 v12, v2
	v_mov_b32_e32 v13, v2
	v_mov_b32_e32 v10, v2
	v_mov_b32_e32 v11, v2
	v_mov_b32_e32 v8, v2
	v_mov_b32_e32 v9, v2
	v_mov_b32_e32 v6, v2
	v_mov_b32_e32 v7, v2
	v_mov_b32_e32 v4, v2
	v_mov_b32_e32 v5, v2
	global_load_dword v128, v[14:15], off offset:-2048
	global_load_dword v129, v[14:15], off offset:-1024
	global_load_dword v130, v[14:15], off
	global_load_dword v131, v[14:15], off offset:1024
	v_lshl_add_u64 v[14:15], v[14:15], 0, s[64:65]
	s_add_i32 s5, s4, 16
	v_mov_b32_e32 v1, s5
	ds_read_b128 v[132:135], v1 offset:0
	ds_read_b128 v[136:139], v1 offset:16
	ds_read_b128 v[140:143], v1 offset:32
	ds_read_b128 v[144:147], v1 offset:48
.LBB0_635:
	s_waitcnt vmcnt(0)
	v_mov_b32_e32 v120, v128
	v_mov_b32_e32 v122, v129
	v_mov_b32_e32 v124, v130
	v_mov_b32_e32 v126, v131
	s_addk_i32 s4, 0x100
	s_cmpk_lg_i32 s4, 0x2000
	s_cbranch_scc0 .Ldq_nopf
	global_load_dword v128, v[14:15], off offset:-2048
	global_load_dword v129, v[14:15], off offset:-1024
	global_load_dword v130, v[14:15], off
	global_load_dword v131, v[14:15], off offset:1024
	v_lshl_add_u64 v[14:15], v[14:15], 0, s[64:65]
.Ldq_nopf:
	ds_read_b128 v[148:151], v1 offset:64
	ds_read_b128 v[152:155], v1 offset:80
	ds_read_b128 v[166:169], v1 offset:96
	ds_read_b128 v[170:173], v1 offset:112
	s_waitcnt lgkmcnt(4)
	v_pk_fma_f32 v[18:19], v[120:121], v[132:133], v[18:19] op_sel_hi:[0,1,1]
	v_pk_fma_f32 v[16:17], v[120:121], v[134:135], v[16:17] op_sel_hi:[0,1,1]
	v_pk_fma_f32 v[12:13], v[120:121], v[136:137], v[12:13] op_sel_hi:[0,1,1]
	v_pk_fma_f32 v[10:11], v[120:121], v[138:139], v[10:11] op_sel_hi:[0,1,1]
	v_pk_fma_f32 v[8:9], v[120:121], v[140:141], v[8:9] op_sel_hi:[0,1,1]
	v_pk_fma_f32 v[6:7], v[120:121], v[142:143], v[6:7] op_sel_hi:[0,1,1]
	v_pk_fma_f32 v[4:5], v[120:121], v[144:145], v[4:5] op_sel_hi:[0,1,1]
	v_pk_fma_f32 v[2:3], v[120:121], v[146:147], v[2:3] op_sel_hi:[0,1,1]
	ds_read_b128 v[132:135], v1 offset:128
	ds_read_b128 v[136:139], v1 offset:144
	ds_read_b128 v[140:143], v1 offset:160
	ds_read_b128 v[144:147], v1 offset:176
	s_waitcnt lgkmcnt(4)
	v_pk_fma_f32 v[18:19], v[122:123], v[148:149], v[18:19] op_sel_hi:[0,1,1]
	v_pk_fma_f32 v[16:17], v[122:123], v[150:151], v[16:17] op_sel_hi:[0,1,1]
	v_pk_fma_f32 v[12:13], v[122:123], v[152:153], v[12:13] op_sel_hi:[0,1,1]
	v_pk_fma_f32 v[10:11], v[122:123], v[154:155], v[10:11] op_sel_hi:[0,1,1]
	v_pk_fma_f32 v[8:9], v[122:123], v[166:167], v[8:9] op_sel_hi:[0,1,1]
	v_pk_fma_f32 v[6:7], v[122:123], v[168:169], v[6:7] op_sel_hi:[0,1,1]
	v_pk_fma_f32 v[4:5], v[122:123], v[170:171], v[4:5] op_sel_hi:[0,1,1]
	v_pk_fma_f32 v[2:3], v[122:123], v[172:173], v[2:3] op_sel_hi:[0,1,1]
	ds_read_b128 v[148:151], v1 offset:192
	ds_read_b128 v[152:155], v1 offset:208
	ds_read_b128 v[166:169], v1 offset:224
	ds_read_b128 v[170:173], v1 offset:240
	s_waitcnt lgkmcnt(4)
	v_pk_fma_f32 v[18:19], v[124:125], v[132:133], v[18:19] op_sel_hi:[0,1,1]
	v_pk_fma_f32 v[16:17], v[124:125], v[134:135], v[16:17] op_sel_hi:[0,1,1]
	v_pk_fma_f32 v[12:13], v[124:125], v[136:137], v[12:13] op_sel_hi:[0,1,1]
	v_pk_fma_f32 v[10:11], v[124:125], v[138:139], v[10:11] op_sel_hi:[0,1,1]
	v_pk_fma_f32 v[8:9], v[124:125], v[140:141], v[8:9] op_sel_hi:[0,1,1]
	v_pk_fma_f32 v[6:7], v[124:125], v[142:143], v[6:7] op_sel_hi:[0,1,1]
	v_pk_fma_f32 v[4:5], v[124:125], v[144:145], v[4:5] op_sel_hi:[0,1,1]
	v_pk_fma_f32 v[2:3], v[124:125], v[146:147], v[2:3] op_sel_hi:[0,1,1]
	ds_read_b128 v[132:135], v1 offset:256
	ds_read_b128 v[136:139], v1 offset:272
	ds_read_b128 v[140:143], v1 offset:288
	ds_read_b128 v[144:147], v1 offset:304
	s_waitcnt lgkmcnt(4)
	v_pk_fma_f32 v[18:19], v[126:127], v[148:149], v[18:19] op_sel_hi:[0,1,1]
	v_pk_fma_f32 v[16:17], v[126:127], v[150:151], v[16:17] op_sel_hi:[0,1,1]
	v_pk_fma_f32 v[12:13], v[126:127], v[152:153], v[12:13] op_sel_hi:[0,1,1]
	v_pk_fma_f32 v[10:11], v[126:127], v[154:155], v[10:11] op_sel_hi:[0,1,1]
	v_pk_fma_f32 v[8:9], v[126:127], v[166:167], v[8:9] op_sel_hi:[0,1,1]
	v_pk_fma_f32 v[6:7], v[126:127], v[168:169], v[6:7] op_sel_hi:[0,1,1]
	v_pk_fma_f32 v[4:5], v[126:127], v[170:171], v[4:5] op_sel_hi:[0,1,1]
	v_pk_fma_f32 v[2:3], v[126:127], v[172:173], v[2:3] op_sel_hi:[0,1,1]
	v_add_u32_e32 v1, 0x100, v1
	s_cbranch_scc1 .LBB0_635
	s_waitcnt lgkmcnt(0)
	v_lshlrev_b32_e32 v14, 16, v23
	v_lshlrev_b32_e32 v15, 16, v99
	v_add_f32_e32 v23, v15, v14
	v_lshlrev_b32_e32 v14, 16, v25
	v_lshlrev_b32_e32 v15, 16, v98
	v_add_f32_e32 v25, v15, v14
	v_lshlrev_b32_e32 v14, 16, v31
	v_lshlrev_b32_e32 v15, 16, v97
	v_add_f32_e32 v31, v15, v14
	v_lshlrev_b32_e32 v14, 16, v33
	v_lshlrev_b32_e32 v15, 16, v96
	v_add_f32_e32 v33, v15, v14
	v_lshlrev_b32_e32 v14, 16, v42
	v_lshlrev_b32_e32 v15, 16, v95
	v_add_f32_e32 v42, v15, v14
	v_lshlrev_b32_e32 v14, 16, v44
	v_lshlrev_b32_e32 v15, 16, v94
	v_add_f32_e32 v44, v15, v14
	v_lshlrev_b32_e32 v14, 16, v51
	v_lshlrev_b32_e32 v15, 16, v93
	v_add_f32_e32 v51, v15, v14
	v_lshlrev_b32_e32 v14, 16, v53
	v_lshlrev_b32_e32 v15, 16, v92
	v_add_f32_e32 v53, v15, v14
	v_lshlrev_b32_e32 v14, 16, v59
	v_lshlrev_b32_e32 v15, 16, v91
	v_add_f32_e32 v59, v15, v14
	v_lshlrev_b32_e32 v14, 16, v61
	v_lshlrev_b32_e32 v15, 16, v90
	v_add_f32_e32 v61, v15, v14
	v_lshlrev_b32_e32 v14, 16, v78
	v_lshlrev_b32_e32 v15, 16, v89
	v_add_f32_e32 v78, v15, v14
	v_lshlrev_b32_e32 v14, 16, v85
	v_lshlrev_b32_e32 v15, 16, v86
	v_add_f32_e32 v85, v15, v14
	v_lshlrev_b32_e32 v14, 16, v79
	v_lshlrev_b32_e32 v15, 16, v80
	v_add_f32_e32 v79, v15, v14
	v_lshlrev_b32_e32 v14, 16, v71
	v_lshlrev_b32_e32 v15, 16, v72
	v_add_f32_e32 v71, v15, v14
	v_lshlrev_b32_e32 v14, 16, v65
	v_lshlrev_b32_e32 v15, 16, v66
	v_add_f32_e32 v65, v15, v14
	v_lshlrev_b32_e32 v14, 16, v34
	v_lshlrev_b32_e32 v15, 16, v35
	v_add_f32_e32 v66, v15, v14
	v_add_u32_e32 v14, s24, v0
	v_ashrrev_i32_e32 v15, 31, v14
	v_readlane_b32 s48, v253, 42
	v_lshlrev_b64 v[14:15], 2, v[14:15]
	v_readlane_b32 s60, v253, 54
	v_readlane_b32 s61, v253, 55
	v_readlane_b32 s62, v253, 56
	v_readlane_b32 s63, v253, 57
	v_lshl_add_u64 v[90:91], s[68:69], 0, v[14:15]
	v_lshlrev_b32_e32 v80, 16, v36
	v_lshl_add_u64 v[34:35], s[62:63], 0, v[14:15]
	v_lshl_add_u64 v[14:15], s[60:61], 0, v[14:15]
	global_load_dword v36, v[14:15], off
	v_lshlrev_b32_e32 v72, 16, v45
	global_load_dword v35, v[34:35], off
	v_add_f32_dpp v14, v66, v66 quad_perm:[1,0,3,2] row_mask:0xf bank_mask:0xf bound_ctrl:1
	global_load_dword v34, v[90:91], off
	v_mul_f32_e32 v72, v80, v72
	v_add_f32_dpp v14, v14, v14 quad_perm:[2,3,0,1] row_mask:0xf bank_mask:0xf bound_ctrl:1
	s_mov_b32 s46, 0x3c800000
	v_lshlrev_b32_e32 v64, 16, v64
	v_add_f32_dpp v14, v14, v14 row_half_mirror row_mask:0xf bank_mask:0xf bound_ctrl:1
	v_lshl_add_u32 v45, v0, 1, 16
	v_lshlrev_b32_e32 v68, 16, v68
	v_add_f32_dpp v14, v14, v14 row_mirror row_mask:0xf bank_mask:0xf bound_ctrl:1
	v_lshlrev_b32_e32 v67, 16, v67
	v_readlane_b32 s13, v14, 16
	v_readlane_b32 s14, v14, 48
	v_readlane_b32 s4, v14, 0
	v_readlane_b32 s5, v14, 32
	v_mov_b32_e32 v14, s13
	v_mov_b32_e32 v15, s14
	v_pk_add_f32 v[14:15], s[4:5], v[14:15]
	v_lshlrev_b32_e32 v69, 16, v69
	v_add_f32_e32 v14, v14, v15
	v_fmac_f32_e32 v66, 0xbc800000, v14
	v_mul_f32_e32 v14, v66, v66
	v_lshlrev_b32_e32 v76, 16, v76
	v_lshlrev_b32_e32 v75, 16, v75
	v_mov_b32_dpp v14, v14 quad_perm:[1,0,3,2] row_mask:0xf bank_mask:0xf bound_ctrl:1
	v_fmac_f32_e32 v14, v66, v66
	v_lshlrev_b32_e32 v77, 16, v77
	v_lshlrev_b32_e32 v82, 16, v82
	v_add_f32_dpp v14, v14, v14 quad_perm:[2,3,0,1] row_mask:0xf bank_mask:0xf bound_ctrl:1
	v_lshlrev_b32_e32 v81, 16, v81
	v_lshlrev_b32_e32 v83, 16, v83
	v_add_f32_dpp v14, v14, v14 row_half_mirror row_mask:0xf bank_mask:0xf bound_ctrl:1
	v_lshlrev_b32_e32 v88, 16, v88
	v_lshlrev_b32_e32 v87, 16, v87
	v_add_f32_dpp v14, v14, v14 row_mirror row_mask:0xf bank_mask:0xf bound_ctrl:1
	v_lshlrev_b32_e32 v84, 16, v84
	v_readlane_b32 s13, v14, 16
	v_readlane_b32 s14, v14, 48
	v_readlane_b32 s4, v14, 0
	v_readlane_b32 s5, v14, 32
	v_mov_b32_e32 v14, s13
	v_mov_b32_e32 v15, s14
	v_pk_add_f32 v[14:15], s[4:5], v[14:15]
	v_lshlrev_b32_e32 v73, 16, v73
	v_mov_b32_e32 v93, v14
	v_lshlrev_b32_e32 v74, 16, v74
	v_lshlrev_b32_e32 v70, 16, v70
	v_lshlrev_b32_e32 v62, 16, v62
	v_lshlrev_b32_e32 v63, 16, v63
	v_lshlrev_b32_e32 v60, 16, v60
	v_lshlrev_b32_e32 v57, 16, v57
	v_lshlrev_b32_e32 v58, 16, v58
	v_lshlrev_b32_e32 v56, 16, v56
	v_lshlrev_b32_e32 v54, 16, v54
	v_lshlrev_b32_e32 v55, 16, v55
	v_lshlrev_b32_e32 v52, 16, v52
	v_lshlrev_b32_e32 v49, 16, v49
	v_lshlrev_b32_e32 v50, 16, v50
	v_lshlrev_b32_e32 v48, 16, v48
	v_lshlrev_b32_e32 v46, 16, v46
	v_lshlrev_b32_e32 v47, 16, v47
	v_lshlrev_b32_e32 v43, 16, v43
	v_lshlrev_b32_e32 v40, 16, v40
	v_lshlrev_b32_e32 v41, 16, v41
	v_lshlrev_b32_e32 v39, 16, v39
	v_lshlrev_b32_e32 v37, 16, v37
	v_lshlrev_b32_e32 v38, 16, v38
	v_lshlrev_b32_e32 v32, 16, v32
	v_lshlrev_b32_e32 v29, 16, v29
	v_lshlrev_b32_e32 v30, 16, v30
	v_lshlrev_b32_e32 v28, 16, v28
	v_lshlrev_b32_e32 v26, 16, v26
	v_lshlrev_b32_e32 v27, 16, v27
	v_lshlrev_b32_e32 v24, 16, v24
	v_lshlrev_b32_e32 v21, 16, v21
	v_lshlrev_b32_e32 v22, 16, v22
	v_lshlrev_b32_e32 v1, 16, v100
	s_waitcnt vmcnt(2)
	v_mul_f32_e32 v80, v72, v36
	v_readlane_b32 s49, v253, 43
	v_readlane_b32 s50, v253, 44
	v_mov_b32_dpp v80, v80 quad_perm:[1,0,3,2] row_mask:0xf bank_mask:0xf bound_ctrl:1
	v_fmac_f32_e32 v80, v72, v36
	v_readlane_b32 s51, v253, 45
	v_readlane_b32 s52, v253, 46
	v_add_f32_dpp v72, v80, v80 quad_perm:[2,3,0,1] row_mask:0xf bank_mask:0xf bound_ctrl:1
	v_readlane_b32 s53, v253, 47
	v_readlane_b32 s54, v253, 48
	v_add_f32_dpp v72, v72, v72 row_half_mirror row_mask:0xf bank_mask:0xf bound_ctrl:1
	v_readlane_b32 s55, v253, 49
	v_readlane_b32 s56, v253, 50
	v_add_f32_dpp v72, v72, v72 row_mirror row_mask:0xf bank_mask:0xf bound_ctrl:1
	v_readlane_b32 s57, v253, 51
	v_readlane_b32 s5, v72, 16
	v_readlane_b32 s4, v72, 0
	v_readlane_b32 s58, v253, 52
	v_mov_b32_e32 v80, s5
	v_readlane_b32 s5, v72, 48
	v_add_f32_e32 v80, s4, v80
	v_readlane_b32 s4, v72, 32
	v_mov_b32_e32 v72, s5
	v_readlane_b32 s59, v253, 53
	v_add_f32_e32 v72, s4, v72
	v_add_f32_e32 v72, v80, v72
	v_add_f32_dpp v80, v65, v65 quad_perm:[1,0,3,2] row_mask:0xf bank_mask:0xf bound_ctrl:1
	s_nop 1
	v_add_f32_dpp v80, v80, v80 quad_perm:[2,3,0,1] row_mask:0xf bank_mask:0xf bound_ctrl:1
	s_nop 1
	v_add_f32_dpp v80, v80, v80 row_half_mirror row_mask:0xf bank_mask:0xf bound_ctrl:1
	s_nop 1
	v_add_f32_dpp v80, v80, v80 row_mirror row_mask:0xf bank_mask:0xf bound_ctrl:1
	s_nop 0
	v_readlane_b32 s13, v80, 16
	v_readlane_b32 s14, v80, 48
	v_readlane_b32 s4, v80, 0
	v_readlane_b32 s5, v80, 32
	v_mov_b32_e32 v90, s13
	v_mov_b32_e32 v91, s14
	v_pk_add_f32 v[90:91], s[4:5], v[90:91]
	s_nop 0
	v_add_f32_e32 v80, v90, v91
	v_fmac_f32_e32 v65, 0xbc800000, v80
	v_mul_f32_e32 v80, v65, v65
	s_nop 1
	v_mov_b32_dpp v80, v80 quad_perm:[1,0,3,2] row_mask:0xf bank_mask:0xf bound_ctrl:1
	v_fmac_f32_e32 v80, v65, v65
	s_nop 1
	v_add_f32_dpp v80, v80, v80 quad_perm:[2,3,0,1] row_mask:0xf bank_mask:0xf bound_ctrl:1
	s_nop 1
	v_add_f32_dpp v80, v80, v80 row_half_mirror row_mask:0xf bank_mask:0xf bound_ctrl:1
	s_nop 1
	v_add_f32_dpp v80, v80, v80 row_mirror row_mask:0xf bank_mask:0xf bound_ctrl:1
	s_nop 0
	v_readlane_b32 s13, v80, 16
	v_readlane_b32 s14, v80, 48
	v_readlane_b32 s4, v80, 0
	v_readlane_b32 s5, v80, 32
	v_mov_b32_e32 v90, s13
	v_mov_b32_e32 v91, s14
	v_pk_add_f32 v[90:91], s[4:5], v[90:91]
	s_mov_b32 s4, 0x3a27c5ac
	v_mov_b32_e32 v92, v90
	v_mov_b32_e32 v14, v91
	v_pk_add_f32 v[90:91], v[92:93], v[14:15]
	v_mov_b64_e32 v[14:15], s[4:5]
	v_pk_fma_f32 v[90:91], v[90:91], s[46:47], v[14:15] op_sel_hi:[1,0,0]
	s_nop 0
	v_mul_f32_e32 v80, 0x4b800000, v91
	v_cmp_gt_f32_e64 s[4:5], s44, v91
	v_cmp_gt_f32_e32 vcc, s44, v90
	s_nop 0
	v_cndmask_b32_e64 v80, v91, v80, s[4:5]
	v_rsq_f32_e32 v80, v80
	s_nop 0
	v_mul_f32_e32 v86, 0x45800000, v80
	v_cndmask_b32_e64 v80, v80, v86, s[4:5]
	v_mul_f32_e32 v66, v66, v80
	s_waitcnt vmcnt(0)
	v_fma_f32 v66, v35, v66, v34
	v_fmac_f32_e32 v66, v72, v64
	v_mul_f32_e32 v18, v18, v66
	v_cvt_pk_bf16_f32 v18, v18, s0
	ds_write_b16 v45, v18 offset:8192
	v_mul_f32_e32 v18, 0x4b800000, v90
	v_cndmask_b32_e32 v18, v90, v18, vcc
	v_rsq_f32_e32 v18, v18
	s_nop 0
	v_mul_f32_e32 v64, 0x45800000, v18
	v_cndmask_b32_e32 v18, v18, v64, vcc
	v_mul_f32_e32 v64, v67, v68
	v_mul_f32_e32 v18, v65, v18
	v_mul_f32_e32 v65, v64, v36
	v_fma_f32 v18, v35, v18, v34
	s_nop 0
	v_mov_b32_dpp v65, v65 quad_perm:[1,0,3,2] row_mask:0xf bank_mask:0xf bound_ctrl:1
	v_fmac_f32_e32 v65, v64, v36
	s_nop 1
	v_add_f32_dpp v64, v65, v65 quad_perm:[2,3,0,1] row_mask:0xf bank_mask:0xf bound_ctrl:1
	s_nop 1
	v_add_f32_dpp v64, v64, v64 row_half_mirror row_mask:0xf bank_mask:0xf bound_ctrl:1
	s_nop 1
	v_add_f32_dpp v64, v64, v64 row_mirror row_mask:0xf bank_mask:0xf bound_ctrl:1
	s_nop 0
	v_readlane_b32 s5, v64, 16
	v_readlane_b32 s4, v64, 0
	s_nop 0
	v_mov_b32_e32 v65, s5
	v_readlane_b32 s5, v64, 48
	v_add_f32_e32 v65, s4, v65
	v_readlane_b32 s4, v64, 32
	v_mov_b32_e32 v64, s5
	s_nop 0
	v_add_f32_e32 v64, s4, v64
	v_add_f32_e32 v64, v65, v64
	v_fmac_f32_e32 v18, v64, v69
	v_mul_f32_e32 v18, v19, v18
	v_cvt_pk_bf16_f32 v18, v18, s0
	ds_write_b16 v45, v18 offset:8704
	v_mul_f32_e32 v64, v75, v76
	v_add_f32_dpp v18, v71, v71 quad_perm:[1,0,3,2] row_mask:0xf bank_mask:0xf bound_ctrl:1
	v_mul_f32_e32 v65, v64, v36
	s_nop 0
	v_add_f32_dpp v18, v18, v18 quad_perm:[2,3,0,1] row_mask:0xf bank_mask:0xf bound_ctrl:1
	v_mov_b32_dpp v65, v65 quad_perm:[1,0,3,2] row_mask:0xf bank_mask:0xf bound_ctrl:1
	v_fmac_f32_e32 v65, v64, v36
	v_add_f32_dpp v18, v18, v18 row_half_mirror row_mask:0xf bank_mask:0xf bound_ctrl:1
	s_nop 0
	v_add_f32_dpp v64, v65, v65 quad_perm:[2,3,0,1] row_mask:0xf bank_mask:0xf bound_ctrl:1
	v_add_f32_dpp v18, v18, v18 row_mirror row_mask:0xf bank_mask:0xf bound_ctrl:1
	s_nop 0
	v_readlane_b32 s13, v18, 16
	v_readlane_b32 s14, v18, 48
	v_readlane_b32 s4, v18, 0
	v_readlane_b32 s5, v18, 32
	v_mov_b32_e32 v18, s13
	v_mov_b32_e32 v19, s14
	v_pk_add_f32 v[18:19], s[4:5], v[18:19]
	v_add_f32_dpp v64, v64, v64 row_half_mirror row_mask:0xf bank_mask:0xf bound_ctrl:1
	v_add_f32_e32 v18, v18, v19
	v_fmac_f32_e32 v71, 0xbc800000, v18
	v_mul_f32_e32 v18, v71, v71
	v_add_f32_dpp v64, v64, v64 row_mirror row_mask:0xf bank_mask:0xf bound_ctrl:1
	s_nop 0
	v_mov_b32_dpp v18, v18 quad_perm:[1,0,3,2] row_mask:0xf bank_mask:0xf bound_ctrl:1
	v_fmac_f32_e32 v18, v71, v71
	s_nop 1
	v_add_f32_dpp v18, v18, v18 quad_perm:[2,3,0,1] row_mask:0xf bank_mask:0xf bound_ctrl:1
	s_nop 1
	v_add_f32_dpp v18, v18, v18 row_half_mirror row_mask:0xf bank_mask:0xf bound_ctrl:1
	s_nop 1
	v_add_f32_dpp v18, v18, v18 row_mirror row_mask:0xf bank_mask:0xf bound_ctrl:1
	s_nop 0
	v_readlane_b32 s13, v18, 16
	v_readlane_b32 s14, v18, 48
	v_readlane_b32 s4, v18, 0
	v_readlane_b32 s5, v18, 32
	v_mov_b32_e32 v18, s13
	v_mov_b32_e32 v19, s14
	v_pk_add_f32 v[18:19], s[4:5], v[18:19]
	v_readlane_b32 s5, v64, 16
	v_readlane_b32 s4, v64, 0
	v_mov_b32_e32 v67, v18
	v_mov_b32_e32 v65, s5
	v_readlane_b32 s5, v64, 48
	v_add_f32_e32 v65, s4, v65
	v_readlane_b32 s4, v64, 32
	v_mov_b32_e32 v64, s5
	s_nop 0
	v_add_f32_e32 v64, s4, v64
	v_add_f32_e32 v68, v65, v64
	s_nop 0
	v_add_f32_dpp v64, v79, v79 quad_perm:[1,0,3,2] row_mask:0xf bank_mask:0xf bound_ctrl:1
	s_nop 1
	v_add_f32_dpp v64, v64, v64 quad_perm:[2,3,0,1] row_mask:0xf bank_mask:0xf bound_ctrl:1
	s_nop 1
	v_add_f32_dpp v64, v64, v64 row_half_mirror row_mask:0xf bank_mask:0xf bound_ctrl:1
	s_nop 1
	v_add_f32_dpp v64, v64, v64 row_mirror row_mask:0xf bank_mask:0xf bound_ctrl:1
	s_nop 0
	v_readlane_b32 s13, v64, 16
	v_readlane_b32 s14, v64, 48
	v_readlane_b32 s4, v64, 0
	v_readlane_b32 s5, v64, 32
	v_mov_b32_e32 v64, s13
	v_mov_b32_e32 v65, s14
	v_pk_add_f32 v[64:65], s[4:5], v[64:65]
	s_nop 0
	v_add_f32_e32 v64, v64, v65
	v_fmac_f32_e32 v79, 0xbc800000, v64
	v_mul_f32_e32 v64, v79, v79
	s_nop 1
	v_mov_b32_dpp v64, v64 quad_perm:[1,0,3,2] row_mask:0xf bank_mask:0xf bound_ctrl:1
	v_fmac_f32_e32 v64, v79, v79
	s_nop 1
	v_add_f32_dpp v64, v64, v64 quad_perm:[2,3,0,1] row_mask:0xf bank_mask:0xf bound_ctrl:1
	s_nop 1
	v_add_f32_dpp v64, v64, v64 row_half_mirror row_mask:0xf bank_mask:0xf bound_ctrl:1
	s_nop 1
	v_add_f32_dpp v64, v64, v64 row_mirror row_mask:0xf bank_mask:0xf bound_ctrl:1
	s_nop 0
	v_readlane_b32 s13, v64, 16
	v_readlane_b32 s14, v64, 48
	v_readlane_b32 s4, v64, 0
	v_readlane_b32 s5, v64, 32
	v_mov_b32_e32 v64, s13
	v_mov_b32_e32 v65, s14
	v_pk_add_f32 v[64:65], s[4:5], v[64:65]
	s_nop 0
	v_mov_b32_e32 v66, v64
	v_mov_b32_e32 v18, v65
	v_pk_add_f32 v[18:19], v[66:67], v[18:19]
	s_nop 0
	v_pk_fma_f32 v[18:19], v[18:19], s[46:47], v[14:15] op_sel_hi:[1,0,0]
	s_nop 0
	v_mul_f32_e32 v64, 0x4b800000, v19
	v_cmp_gt_f32_e64 s[4:5], s44, v19
	v_cmp_gt_f32_e32 vcc, s44, v18
	s_nop 0
	v_cndmask_b32_e64 v19, v19, v64, s[4:5]
	v_rsq_f32_e32 v19, v19
	s_nop 0
	v_mul_f32_e32 v64, 0x45800000, v19
	v_cndmask_b32_e64 v19, v19, v64, s[4:5]
	v_mul_f32_e32 v19, v71, v19
	v_fma_f32 v19, v35, v19, v34
	v_fmac_f32_e32 v19, v68, v77
	v_mul_f32_e32 v16, v16, v19
	v_cvt_pk_bf16_f32 v16, v16, s0
	ds_write_b16 v45, v16 offset:9216
	v_mul_f32_e32 v16, 0x4b800000, v18
	v_cndmask_b32_e32 v16, v18, v16, vcc
	v_rsq_f32_e32 v16, v16
	s_nop 0
	v_mul_f32_e32 v18, 0x45800000, v16
	v_cndmask_b32_e32 v16, v16, v18, vcc
	v_mul_f32_e32 v18, v81, v82
	v_mul_f32_e32 v19, v18, v36
	v_mul_f32_e32 v16, v79, v16
	v_fma_f32 v16, v35, v16, v34
	v_mov_b32_dpp v19, v19 quad_perm:[1,0,3,2] row_mask:0xf bank_mask:0xf bound_ctrl:1
	v_fmac_f32_e32 v19, v18, v36
	s_nop 1
	v_add_f32_dpp v18, v19, v19 quad_perm:[2,3,0,1] row_mask:0xf bank_mask:0xf bound_ctrl:1
	s_nop 1
	v_add_f32_dpp v18, v18, v18 row_half_mirror row_mask:0xf bank_mask:0xf bound_ctrl:1
	s_nop 1
	v_add_f32_dpp v18, v18, v18 row_mirror row_mask:0xf bank_mask:0xf bound_ctrl:1
	s_nop 0
	v_readlane_b32 s5, v18, 16
	v_readlane_b32 s4, v18, 0
	s_nop 0
	v_mov_b32_e32 v19, s5
	v_readlane_b32 s5, v18, 48
	v_add_f32_e32 v19, s4, v19
	v_readlane_b32 s4, v18, 32
	v_mov_b32_e32 v18, s5
	s_nop 0
	v_add_f32_e32 v18, s4, v18
	v_add_f32_e32 v18, v19, v18
	v_fmac_f32_e32 v16, v18, v83
	v_mul_f32_e32 v16, v17, v16
	v_cvt_pk_bf16_f32 v16, v16, s0
	ds_write_b16 v45, v16 offset:9728
	v_mul_f32_e32 v18, v87, v88
	v_add_f32_dpp v16, v85, v85 quad_perm:[1,0,3,2] row_mask:0xf bank_mask:0xf bound_ctrl:1
	v_mul_f32_e32 v19, v18, v36
	s_nop 0
	v_add_f32_dpp v16, v16, v16 quad_perm:[2,3,0,1] row_mask:0xf bank_mask:0xf bound_ctrl:1
	v_mov_b32_dpp v19, v19 quad_perm:[1,0,3,2] row_mask:0xf bank_mask:0xf bound_ctrl:1
	v_fmac_f32_e32 v19, v18, v36
	v_add_f32_dpp v16, v16, v16 row_half_mirror row_mask:0xf bank_mask:0xf bound_ctrl:1
	s_nop 0
	v_add_f32_dpp v18, v19, v19 quad_perm:[2,3,0,1] row_mask:0xf bank_mask:0xf bound_ctrl:1
	v_add_f32_dpp v16, v16, v16 row_mirror row_mask:0xf bank_mask:0xf bound_ctrl:1
	s_nop 0
	v_readlane_b32 s13, v16, 16
	v_readlane_b32 s14, v16, 48
	v_readlane_b32 s4, v16, 0
	v_readlane_b32 s5, v16, 32
	v_mov_b32_e32 v16, s13
	v_mov_b32_e32 v17, s14
	v_pk_add_f32 v[16:17], s[4:5], v[16:17]
	v_add_f32_dpp v18, v18, v18 row_half_mirror row_mask:0xf bank_mask:0xf bound_ctrl:1
	v_add_f32_e32 v16, v16, v17
	v_fmac_f32_e32 v85, 0xbc800000, v16
	v_mul_f32_e32 v16, v85, v85
	v_add_f32_dpp v18, v18, v18 row_mirror row_mask:0xf bank_mask:0xf bound_ctrl:1
	s_nop 0
	v_mov_b32_dpp v16, v16 quad_perm:[1,0,3,2] row_mask:0xf bank_mask:0xf bound_ctrl:1
	v_fmac_f32_e32 v16, v85, v85
	s_nop 1
	v_add_f32_dpp v16, v16, v16 quad_perm:[2,3,0,1] row_mask:0xf bank_mask:0xf bound_ctrl:1
	s_nop 1
	v_add_f32_dpp v16, v16, v16 row_half_mirror row_mask:0xf bank_mask:0xf bound_ctrl:1
	s_nop 1
	v_add_f32_dpp v16, v16, v16 row_mirror row_mask:0xf bank_mask:0xf bound_ctrl:1
	s_nop 0
	v_readlane_b32 s13, v16, 16
	v_readlane_b32 s14, v16, 48
	v_readlane_b32 s4, v16, 0
	v_readlane_b32 s5, v16, 32
	v_mov_b32_e32 v16, s13
	v_mov_b32_e32 v17, s14
	v_pk_add_f32 v[16:17], s[4:5], v[16:17]
	v_readlane_b32 s5, v18, 16
	v_readlane_b32 s4, v18, 0
	v_mov_b32_e32 v65, v16
	v_mov_b32_e32 v19, s5
	v_readlane_b32 s5, v18, 48
	v_add_f32_e32 v19, s4, v19
	v_readlane_b32 s4, v18, 32
	v_mov_b32_e32 v18, s5
	s_nop 0
	v_add_f32_e32 v18, s4, v18
	v_add_f32_e32 v66, v19, v18
	s_nop 0
	v_add_f32_dpp v18, v78, v78 quad_perm:[1,0,3,2] row_mask:0xf bank_mask:0xf bound_ctrl:1
	s_nop 1
	v_add_f32_dpp v18, v18, v18 quad_perm:[2,3,0,1] row_mask:0xf bank_mask:0xf bound_ctrl:1
	s_nop 1
	v_add_f32_dpp v18, v18, v18 row_half_mirror row_mask:0xf bank_mask:0xf bound_ctrl:1
	s_nop 1
	v_add_f32_dpp v18, v18, v18 row_mirror row_mask:0xf bank_mask:0xf bound_ctrl:1
	s_nop 0
	v_readlane_b32 s13, v18, 16
	v_readlane_b32 s14, v18, 48
	v_readlane_b32 s4, v18, 0
	v_readlane_b32 s5, v18, 32
	v_mov_b32_e32 v18, s13
	v_mov_b32_e32 v19, s14
	v_pk_add_f32 v[18:19], s[4:5], v[18:19]
	s_nop 0
	v_add_f32_e32 v18, v18, v19
	v_fmac_f32_e32 v78, 0xbc800000, v18
	v_mul_f32_e32 v18, v78, v78
	s_nop 1
	v_mov_b32_dpp v18, v18 quad_perm:[1,0,3,2] row_mask:0xf bank_mask:0xf bound_ctrl:1
	v_fmac_f32_e32 v18, v78, v78
	s_nop 1
	v_add_f32_dpp v18, v18, v18 quad_perm:[2,3,0,1] row_mask:0xf bank_mask:0xf bound_ctrl:1
	s_nop 1
	v_add_f32_dpp v18, v18, v18 row_half_mirror row_mask:0xf bank_mask:0xf bound_ctrl:1
	s_nop 1
	v_add_f32_dpp v18, v18, v18 row_mirror row_mask:0xf bank_mask:0xf bound_ctrl:1
	s_nop 0
	v_readlane_b32 s13, v18, 16
	v_readlane_b32 s14, v18, 48
	v_readlane_b32 s4, v18, 0
	v_readlane_b32 s5, v18, 32
	v_mov_b32_e32 v18, s13
	v_mov_b32_e32 v19, s14
	v_pk_add_f32 v[18:19], s[4:5], v[18:19]
	s_nop 0
	v_mov_b32_e32 v64, v18
	v_mov_b32_e32 v16, v19
	v_pk_add_f32 v[16:17], v[64:65], v[16:17]
	s_nop 0
	v_pk_fma_f32 v[16:17], v[16:17], s[46:47], v[14:15] op_sel_hi:[1,0,0]
	s_nop 0
	v_mul_f32_e32 v18, 0x4b800000, v17
	v_cmp_gt_f32_e64 s[4:5], s44, v17
	v_cmp_gt_f32_e32 vcc, s44, v16
	s_nop 0
	v_cndmask_b32_e64 v17, v17, v18, s[4:5]
	v_rsq_f32_e32 v17, v17
	s_nop 0
	v_mul_f32_e32 v18, 0x45800000, v17
	v_cndmask_b32_e64 v17, v17, v18, s[4:5]
	v_mul_f32_e32 v17, v85, v17
	v_fma_f32 v17, v35, v17, v34
	v_fmac_f32_e32 v17, v66, v84
	v_mul_f32_e32 v12, v12, v17
	v_cvt_pk_bf16_f32 v12, v12, s0
	ds_write_b16 v45, v12 offset:10240
	v_mul_f32_e32 v12, 0x4b800000, v16
	v_cndmask_b32_e32 v12, v16, v12, vcc
	v_rsq_f32_e32 v12, v12
	s_nop 0
	v_mul_f32_e32 v16, 0x45800000, v12
	v_cndmask_b32_e32 v12, v12, v16, vcc
	v_mul_f32_e32 v16, v74, v73
	v_mul_f32_e32 v17, v16, v36
	v_mul_f32_e32 v12, v78, v12
	v_fma_f32 v12, v35, v12, v34
	v_mov_b32_dpp v17, v17 quad_perm:[1,0,3,2] row_mask:0xf bank_mask:0xf bound_ctrl:1
	v_fmac_f32_e32 v17, v16, v36
	s_nop 1
	v_add_f32_dpp v16, v17, v17 quad_perm:[2,3,0,1] row_mask:0xf bank_mask:0xf bound_ctrl:1
	s_nop 1
	v_add_f32_dpp v16, v16, v16 row_half_mirror row_mask:0xf bank_mask:0xf bound_ctrl:1
	s_nop 1
	v_add_f32_dpp v16, v16, v16 row_mirror row_mask:0xf bank_mask:0xf bound_ctrl:1
	s_nop 0
	v_readlane_b32 s5, v16, 16
	v_readlane_b32 s4, v16, 0
	s_nop 0
	v_mov_b32_e32 v17, s5
	v_readlane_b32 s5, v16, 48
	v_add_f32_e32 v17, s4, v17
	v_readlane_b32 s4, v16, 32
	v_mov_b32_e32 v16, s5
	s_nop 0
	v_add_f32_e32 v16, s4, v16
	v_add_f32_e32 v16, v17, v16
	v_fmac_f32_e32 v12, v16, v70
	v_mul_f32_e32 v12, v13, v12
	v_cvt_pk_bf16_f32 v12, v12, s0
	ds_write_b16 v45, v12 offset:10752
	v_mul_f32_e32 v16, v63, v62
	v_add_f32_dpp v12, v61, v61 quad_perm:[1,0,3,2] row_mask:0xf bank_mask:0xf bound_ctrl:1
	v_mul_f32_e32 v17, v16, v36
	s_nop 0
	v_add_f32_dpp v12, v12, v12 quad_perm:[2,3,0,1] row_mask:0xf bank_mask:0xf bound_ctrl:1
	v_mov_b32_dpp v17, v17 quad_perm:[1,0,3,2] row_mask:0xf bank_mask:0xf bound_ctrl:1
	v_fmac_f32_e32 v17, v16, v36
	v_add_f32_dpp v12, v12, v12 row_half_mirror row_mask:0xf bank_mask:0xf bound_ctrl:1
	s_nop 0
	v_add_f32_dpp v16, v17, v17 quad_perm:[2,3,0,1] row_mask:0xf bank_mask:0xf bound_ctrl:1
	v_add_f32_dpp v12, v12, v12 row_mirror row_mask:0xf bank_mask:0xf bound_ctrl:1
	s_nop 0
	v_readlane_b32 s13, v12, 16
	v_readlane_b32 s14, v12, 48
	v_readlane_b32 s4, v12, 0
	v_readlane_b32 s5, v12, 32
	v_mov_b32_e32 v12, s13
	v_mov_b32_e32 v13, s14
	v_pk_add_f32 v[12:13], s[4:5], v[12:13]
	v_add_f32_dpp v16, v16, v16 row_half_mirror row_mask:0xf bank_mask:0xf bound_ctrl:1
	v_add_f32_e32 v12, v12, v13
	v_fmac_f32_e32 v61, 0xbc800000, v12
	v_mul_f32_e32 v12, v61, v61
	v_add_f32_dpp v16, v16, v16 row_mirror row_mask:0xf bank_mask:0xf bound_ctrl:1
	s_nop 0
	v_mov_b32_dpp v12, v12 quad_perm:[1,0,3,2] row_mask:0xf bank_mask:0xf bound_ctrl:1
	v_fmac_f32_e32 v12, v61, v61
	s_nop 1
	v_add_f32_dpp v12, v12, v12 quad_perm:[2,3,0,1] row_mask:0xf bank_mask:0xf bound_ctrl:1
	s_nop 1
	v_add_f32_dpp v12, v12, v12 row_half_mirror row_mask:0xf bank_mask:0xf bound_ctrl:1
	s_nop 1
	v_add_f32_dpp v12, v12, v12 row_mirror row_mask:0xf bank_mask:0xf bound_ctrl:1
	s_nop 0
	v_readlane_b32 s13, v12, 16
	v_readlane_b32 s14, v12, 48
	v_readlane_b32 s4, v12, 0
	v_readlane_b32 s5, v12, 32
	v_mov_b32_e32 v12, s13
	v_mov_b32_e32 v13, s14
	v_pk_add_f32 v[12:13], s[4:5], v[12:13]
	v_readlane_b32 s5, v16, 16
	v_readlane_b32 s4, v16, 0
	v_mov_b32_e32 v19, v12
	v_mov_b32_e32 v17, s5
	v_readlane_b32 s5, v16, 48
	v_add_f32_e32 v17, s4, v17
	v_readlane_b32 s4, v16, 32
	v_mov_b32_e32 v16, s5
	s_nop 0
	v_add_f32_e32 v16, s4, v16
	v_add_f32_e32 v62, v17, v16
	s_nop 0
	v_add_f32_dpp v16, v59, v59 quad_perm:[1,0,3,2] row_mask:0xf bank_mask:0xf bound_ctrl:1
	s_nop 1
	v_add_f32_dpp v16, v16, v16 quad_perm:[2,3,0,1] row_mask:0xf bank_mask:0xf bound_ctrl:1
	s_nop 1
	v_add_f32_dpp v16, v16, v16 row_half_mirror row_mask:0xf bank_mask:0xf bound_ctrl:1
	s_nop 1
	v_add_f32_dpp v16, v16, v16 row_mirror row_mask:0xf bank_mask:0xf bound_ctrl:1
	s_nop 0
	v_readlane_b32 s13, v16, 16
	v_readlane_b32 s14, v16, 48
	v_readlane_b32 s4, v16, 0
	v_readlane_b32 s5, v16, 32
	v_mov_b32_e32 v16, s13
	v_mov_b32_e32 v17, s14
	v_pk_add_f32 v[16:17], s[4:5], v[16:17]
	s_nop 0
	v_add_f32_e32 v16, v16, v17
	v_fmac_f32_e32 v59, 0xbc800000, v16
	v_mul_f32_e32 v16, v59, v59
	s_nop 1
	v_mov_b32_dpp v16, v16 quad_perm:[1,0,3,2] row_mask:0xf bank_mask:0xf bound_ctrl:1
	v_fmac_f32_e32 v16, v59, v59
	s_nop 1
	v_add_f32_dpp v16, v16, v16 quad_perm:[2,3,0,1] row_mask:0xf bank_mask:0xf bound_ctrl:1
	s_nop 1
	v_add_f32_dpp v16, v16, v16 row_half_mirror row_mask:0xf bank_mask:0xf bound_ctrl:1
	s_nop 1
	v_add_f32_dpp v16, v16, v16 row_mirror row_mask:0xf bank_mask:0xf bound_ctrl:1
	s_nop 0
	v_readlane_b32 s13, v16, 16
	v_readlane_b32 s14, v16, 48
	v_readlane_b32 s4, v16, 0
	v_readlane_b32 s5, v16, 32
	v_mov_b32_e32 v16, s13
	v_mov_b32_e32 v17, s14
	v_pk_add_f32 v[16:17], s[4:5], v[16:17]
	s_nop 0
	v_mov_b32_e32 v18, v16
	v_mov_b32_e32 v12, v17
	v_pk_add_f32 v[12:13], v[18:19], v[12:13]
	s_nop 0
	v_pk_fma_f32 v[12:13], v[12:13], s[46:47], v[14:15] op_sel_hi:[1,0,0]
	s_nop 0
	v_mul_f32_e32 v16, 0x4b800000, v13
	v_cmp_gt_f32_e64 s[4:5], s44, v13
	v_cmp_gt_f32_e32 vcc, s44, v12
	s_nop 0
	v_cndmask_b32_e64 v13, v13, v16, s[4:5]
	v_rsq_f32_e32 v13, v13
	s_nop 0
	v_mul_f32_e32 v16, 0x45800000, v13
	v_cndmask_b32_e64 v13, v13, v16, s[4:5]
	v_mul_f32_e32 v13, v61, v13
	v_fma_f32 v13, v35, v13, v34
	v_fmac_f32_e32 v13, v62, v60
	v_mul_f32_e32 v10, v10, v13
	v_cvt_pk_bf16_f32 v10, v10, s0
	ds_write_b16 v45, v10 offset:11264
	v_mul_f32_e32 v10, 0x4b800000, v12
	v_cndmask_b32_e32 v10, v12, v10, vcc
	v_rsq_f32_e32 v10, v10
	s_nop 0
	v_mul_f32_e32 v12, 0x45800000, v10
	v_cndmask_b32_e32 v10, v10, v12, vcc
	v_mul_f32_e32 v12, v58, v57
	v_mul_f32_e32 v13, v12, v36
	v_mul_f32_e32 v10, v59, v10
	v_fma_f32 v10, v35, v10, v34
	v_mov_b32_dpp v13, v13 quad_perm:[1,0,3,2] row_mask:0xf bank_mask:0xf bound_ctrl:1
	v_fmac_f32_e32 v13, v12, v36
	s_nop 1
	v_add_f32_dpp v12, v13, v13 quad_perm:[2,3,0,1] row_mask:0xf bank_mask:0xf bound_ctrl:1
	s_nop 1
	v_add_f32_dpp v12, v12, v12 row_half_mirror row_mask:0xf bank_mask:0xf bound_ctrl:1
	s_nop 1
	v_add_f32_dpp v12, v12, v12 row_mirror row_mask:0xf bank_mask:0xf bound_ctrl:1
	s_nop 0
	v_readlane_b32 s5, v12, 16
	v_readlane_b32 s4, v12, 0
	s_nop 0
	v_mov_b32_e32 v13, s5
	v_readlane_b32 s5, v12, 48
	v_add_f32_e32 v13, s4, v13
	v_readlane_b32 s4, v12, 32
	v_mov_b32_e32 v12, s5
	s_nop 0
	v_add_f32_e32 v12, s4, v12
	v_add_f32_e32 v12, v13, v12
	v_fmac_f32_e32 v10, v12, v56
	v_mul_f32_e32 v10, v11, v10
	v_cvt_pk_bf16_f32 v10, v10, s0
	ds_write_b16 v45, v10 offset:11776
	v_mul_f32_e32 v12, v55, v54
	v_add_f32_dpp v10, v53, v53 quad_perm:[1,0,3,2] row_mask:0xf bank_mask:0xf bound_ctrl:1
	v_mul_f32_e32 v13, v12, v36
	s_nop 0
	v_add_f32_dpp v10, v10, v10 quad_perm:[2,3,0,1] row_mask:0xf bank_mask:0xf bound_ctrl:1
	v_mov_b32_dpp v13, v13 quad_perm:[1,0,3,2] row_mask:0xf bank_mask:0xf bound_ctrl:1
	v_fmac_f32_e32 v13, v12, v36
	v_add_f32_dpp v10, v10, v10 row_half_mirror row_mask:0xf bank_mask:0xf bound_ctrl:1
	s_nop 0
	v_add_f32_dpp v12, v13, v13 quad_perm:[2,3,0,1] row_mask:0xf bank_mask:0xf bound_ctrl:1
	v_add_f32_dpp v10, v10, v10 row_mirror row_mask:0xf bank_mask:0xf bound_ctrl:1
	s_nop 0
	v_readlane_b32 s13, v10, 16
	v_readlane_b32 s14, v10, 48
	v_readlane_b32 s4, v10, 0
	v_readlane_b32 s5, v10, 32
	v_mov_b32_e32 v10, s13
	v_mov_b32_e32 v11, s14
	v_pk_add_f32 v[10:11], s[4:5], v[10:11]
	v_add_f32_dpp v12, v12, v12 row_half_mirror row_mask:0xf bank_mask:0xf bound_ctrl:1
	v_add_f32_e32 v10, v10, v11
	v_fmac_f32_e32 v53, 0xbc800000, v10
	v_mul_f32_e32 v10, v53, v53
	v_add_f32_dpp v12, v12, v12 row_mirror row_mask:0xf bank_mask:0xf bound_ctrl:1
	s_nop 0
	v_mov_b32_dpp v10, v10 quad_perm:[1,0,3,2] row_mask:0xf bank_mask:0xf bound_ctrl:1
	v_fmac_f32_e32 v10, v53, v53
	s_nop 1
	v_add_f32_dpp v10, v10, v10 quad_perm:[2,3,0,1] row_mask:0xf bank_mask:0xf bound_ctrl:1
	s_nop 1
	v_add_f32_dpp v10, v10, v10 row_half_mirror row_mask:0xf bank_mask:0xf bound_ctrl:1
	s_nop 1
	v_add_f32_dpp v10, v10, v10 row_mirror row_mask:0xf bank_mask:0xf bound_ctrl:1
	s_nop 0
	v_readlane_b32 s13, v10, 16
	v_readlane_b32 s14, v10, 48
	v_readlane_b32 s4, v10, 0
	v_readlane_b32 s5, v10, 32
	v_mov_b32_e32 v10, s13
	v_mov_b32_e32 v11, s14
	v_pk_add_f32 v[10:11], s[4:5], v[10:11]
	v_readlane_b32 s5, v12, 16
	v_readlane_b32 s4, v12, 0
	v_mov_b32_e32 v17, v10
	v_mov_b32_e32 v13, s5
	v_readlane_b32 s5, v12, 48
	v_add_f32_e32 v13, s4, v13
	v_readlane_b32 s4, v12, 32
	v_mov_b32_e32 v12, s5
	s_nop 0
	v_add_f32_e32 v12, s4, v12
	v_add_f32_e32 v18, v13, v12
	s_nop 0
	v_add_f32_dpp v12, v51, v51 quad_perm:[1,0,3,2] row_mask:0xf bank_mask:0xf bound_ctrl:1
	s_nop 1
	v_add_f32_dpp v12, v12, v12 quad_perm:[2,3,0,1] row_mask:0xf bank_mask:0xf bound_ctrl:1
	s_nop 1
	v_add_f32_dpp v12, v12, v12 row_half_mirror row_mask:0xf bank_mask:0xf bound_ctrl:1
	s_nop 1
	v_add_f32_dpp v12, v12, v12 row_mirror row_mask:0xf bank_mask:0xf bound_ctrl:1
	s_nop 0
	v_readlane_b32 s13, v12, 16
	v_readlane_b32 s14, v12, 48
	v_readlane_b32 s4, v12, 0
	v_readlane_b32 s5, v12, 32
	v_mov_b32_e32 v12, s13
	v_mov_b32_e32 v13, s14
	v_pk_add_f32 v[12:13], s[4:5], v[12:13]
	s_nop 0
	v_add_f32_e32 v12, v12, v13
	v_fmac_f32_e32 v51, 0xbc800000, v12
	v_mul_f32_e32 v12, v51, v51
	s_nop 1
	v_mov_b32_dpp v12, v12 quad_perm:[1,0,3,2] row_mask:0xf bank_mask:0xf bound_ctrl:1
	v_fmac_f32_e32 v12, v51, v51
	s_nop 1
	v_add_f32_dpp v12, v12, v12 quad_perm:[2,3,0,1] row_mask:0xf bank_mask:0xf bound_ctrl:1
	s_nop 1
	v_add_f32_dpp v12, v12, v12 row_half_mirror row_mask:0xf bank_mask:0xf bound_ctrl:1
	s_nop 1
	v_add_f32_dpp v12, v12, v12 row_mirror row_mask:0xf bank_mask:0xf bound_ctrl:1
	s_nop 0
	v_readlane_b32 s13, v12, 16
	v_readlane_b32 s14, v12, 48
	v_readlane_b32 s4, v12, 0
	v_readlane_b32 s5, v12, 32
	v_mov_b32_e32 v12, s13
	v_mov_b32_e32 v13, s14
	v_pk_add_f32 v[12:13], s[4:5], v[12:13]
	s_nop 0
	v_mov_b32_e32 v16, v12
	v_mov_b32_e32 v10, v13
	v_pk_add_f32 v[10:11], v[16:17], v[10:11]
	s_nop 0
	v_pk_fma_f32 v[10:11], v[10:11], s[46:47], v[14:15] op_sel_hi:[1,0,0]
	s_nop 0
	v_mul_f32_e32 v12, 0x4b800000, v11
	v_cmp_gt_f32_e64 s[4:5], s44, v11
	v_cmp_gt_f32_e32 vcc, s44, v10
	s_nop 0
	v_cndmask_b32_e64 v11, v11, v12, s[4:5]
	v_rsq_f32_e32 v11, v11
	s_nop 0
	v_mul_f32_e32 v12, 0x45800000, v11
	v_cndmask_b32_e64 v11, v11, v12, s[4:5]
	v_mul_f32_e32 v11, v53, v11
	v_fma_f32 v11, v35, v11, v34
	v_fmac_f32_e32 v11, v18, v52
	v_mul_f32_e32 v8, v8, v11
	v_cvt_pk_bf16_f32 v8, v8, s0
	ds_write_b16 v45, v8 offset:12288
	v_mul_f32_e32 v8, 0x4b800000, v10
	v_cndmask_b32_e32 v8, v10, v8, vcc
	v_rsq_f32_e32 v8, v8
	s_nop 0
	v_mul_f32_e32 v10, 0x45800000, v8
	v_cndmask_b32_e32 v8, v8, v10, vcc
	v_mul_f32_e32 v10, v50, v49
	v_mul_f32_e32 v11, v10, v36
	v_mul_f32_e32 v8, v51, v8
	v_fma_f32 v8, v35, v8, v34
	v_mov_b32_dpp v11, v11 quad_perm:[1,0,3,2] row_mask:0xf bank_mask:0xf bound_ctrl:1
	v_fmac_f32_e32 v11, v10, v36
	s_nop 1
	v_add_f32_dpp v10, v11, v11 quad_perm:[2,3,0,1] row_mask:0xf bank_mask:0xf bound_ctrl:1
	s_nop 1
	v_add_f32_dpp v10, v10, v10 row_half_mirror row_mask:0xf bank_mask:0xf bound_ctrl:1
	s_nop 1
	v_add_f32_dpp v10, v10, v10 row_mirror row_mask:0xf bank_mask:0xf bound_ctrl:1
	s_nop 0
	v_readlane_b32 s5, v10, 16
	v_readlane_b32 s4, v10, 0
	s_nop 0
	v_mov_b32_e32 v11, s5
	v_readlane_b32 s5, v10, 48
	v_add_f32_e32 v11, s4, v11
	v_readlane_b32 s4, v10, 32
	v_mov_b32_e32 v10, s5
	s_nop 0
	v_add_f32_e32 v10, s4, v10
	v_add_f32_e32 v10, v11, v10
	v_fmac_f32_e32 v8, v10, v48
	v_mul_f32_e32 v8, v9, v8
	v_cvt_pk_bf16_f32 v8, v8, s0
	ds_write_b16 v45, v8 offset:12800
	v_mul_f32_e32 v10, v47, v46
	v_add_f32_dpp v8, v44, v44 quad_perm:[1,0,3,2] row_mask:0xf bank_mask:0xf bound_ctrl:1
	v_mul_f32_e32 v11, v10, v36
	s_nop 0
	v_add_f32_dpp v8, v8, v8 quad_perm:[2,3,0,1] row_mask:0xf bank_mask:0xf bound_ctrl:1
	v_mov_b32_dpp v11, v11 quad_perm:[1,0,3,2] row_mask:0xf bank_mask:0xf bound_ctrl:1
	v_fmac_f32_e32 v11, v10, v36
	v_add_f32_dpp v8, v8, v8 row_half_mirror row_mask:0xf bank_mask:0xf bound_ctrl:1
	s_nop 0
	v_add_f32_dpp v10, v11, v11 quad_perm:[2,3,0,1] row_mask:0xf bank_mask:0xf bound_ctrl:1
	v_add_f32_dpp v8, v8, v8 row_mirror row_mask:0xf bank_mask:0xf bound_ctrl:1
	s_nop 0
	v_readlane_b32 s13, v8, 16
	v_readlane_b32 s14, v8, 48
	v_readlane_b32 s4, v8, 0
	v_readlane_b32 s5, v8, 32
	v_mov_b32_e32 v8, s13
	v_mov_b32_e32 v9, s14
	v_pk_add_f32 v[8:9], s[4:5], v[8:9]
	v_add_f32_dpp v10, v10, v10 row_half_mirror row_mask:0xf bank_mask:0xf bound_ctrl:1
	v_add_f32_e32 v8, v8, v9
	v_fmac_f32_e32 v44, 0xbc800000, v8
	v_mul_f32_e32 v8, v44, v44
	v_add_f32_dpp v10, v10, v10 row_mirror row_mask:0xf bank_mask:0xf bound_ctrl:1
	s_nop 0
	v_mov_b32_dpp v8, v8 quad_perm:[1,0,3,2] row_mask:0xf bank_mask:0xf bound_ctrl:1
	v_fmac_f32_e32 v8, v44, v44
	s_nop 1
	v_add_f32_dpp v8, v8, v8 quad_perm:[2,3,0,1] row_mask:0xf bank_mask:0xf bound_ctrl:1
	s_nop 1
	v_add_f32_dpp v8, v8, v8 row_half_mirror row_mask:0xf bank_mask:0xf bound_ctrl:1
	s_nop 1
	v_add_f32_dpp v8, v8, v8 row_mirror row_mask:0xf bank_mask:0xf bound_ctrl:1
	s_nop 0
	v_readlane_b32 s13, v8, 16
	v_readlane_b32 s14, v8, 48
	v_readlane_b32 s4, v8, 0
	v_readlane_b32 s5, v8, 32
	v_mov_b32_e32 v8, s13
	v_mov_b32_e32 v9, s14
	v_pk_add_f32 v[8:9], s[4:5], v[8:9]
	v_readlane_b32 s5, v10, 16
	v_readlane_b32 s4, v10, 0
	v_mov_b32_e32 v13, v8
	v_mov_b32_e32 v11, s5
	v_readlane_b32 s5, v10, 48
	v_add_f32_e32 v11, s4, v11
	v_readlane_b32 s4, v10, 32
	v_mov_b32_e32 v10, s5
	s_nop 0
	v_add_f32_e32 v10, s4, v10
	v_add_f32_e32 v16, v11, v10
	s_nop 0
	v_add_f32_dpp v10, v42, v42 quad_perm:[1,0,3,2] row_mask:0xf bank_mask:0xf bound_ctrl:1
	s_nop 1
	v_add_f32_dpp v10, v10, v10 quad_perm:[2,3,0,1] row_mask:0xf bank_mask:0xf bound_ctrl:1
	s_nop 1
	v_add_f32_dpp v10, v10, v10 row_half_mirror row_mask:0xf bank_mask:0xf bound_ctrl:1
	s_nop 1
	v_add_f32_dpp v10, v10, v10 row_mirror row_mask:0xf bank_mask:0xf bound_ctrl:1
	s_nop 0
	v_readlane_b32 s13, v10, 16
	v_readlane_b32 s14, v10, 48
	v_readlane_b32 s4, v10, 0
	v_readlane_b32 s5, v10, 32
	v_mov_b32_e32 v10, s13
	v_mov_b32_e32 v11, s14
	v_pk_add_f32 v[10:11], s[4:5], v[10:11]
	s_nop 0
	v_add_f32_e32 v10, v10, v11
	v_fmac_f32_e32 v42, 0xbc800000, v10
	v_mul_f32_e32 v10, v42, v42
	s_nop 1
	v_mov_b32_dpp v10, v10 quad_perm:[1,0,3,2] row_mask:0xf bank_mask:0xf bound_ctrl:1
	v_fmac_f32_e32 v10, v42, v42
	s_nop 1
	v_add_f32_dpp v10, v10, v10 quad_perm:[2,3,0,1] row_mask:0xf bank_mask:0xf bound_ctrl:1
	s_nop 1
	v_add_f32_dpp v10, v10, v10 row_half_mirror row_mask:0xf bank_mask:0xf bound_ctrl:1
	s_nop 1
	v_add_f32_dpp v10, v10, v10 row_mirror row_mask:0xf bank_mask:0xf bound_ctrl:1
	s_nop 0
	v_readlane_b32 s13, v10, 16
	v_readlane_b32 s14, v10, 48
	v_readlane_b32 s4, v10, 0
	v_readlane_b32 s5, v10, 32
	v_mov_b32_e32 v10, s13
	v_mov_b32_e32 v11, s14
	v_pk_add_f32 v[10:11], s[4:5], v[10:11]
	s_nop 0
	v_mov_b32_e32 v12, v10
	v_mov_b32_e32 v8, v11
	v_pk_add_f32 v[8:9], v[12:13], v[8:9]
	s_nop 0
	v_pk_fma_f32 v[8:9], v[8:9], s[46:47], v[14:15] op_sel_hi:[1,0,0]
	s_nop 0
	v_mul_f32_e32 v10, 0x4b800000, v9
	v_cmp_gt_f32_e64 s[4:5], s44, v9
	v_cmp_gt_f32_e32 vcc, s44, v8
	s_nop 0
	v_cndmask_b32_e64 v9, v9, v10, s[4:5]
	v_rsq_f32_e32 v9, v9
	s_nop 0
	v_mul_f32_e32 v10, 0x45800000, v9
	v_cndmask_b32_e64 v9, v9, v10, s[4:5]
	v_mul_f32_e32 v9, v44, v9
	v_fma_f32 v9, v35, v9, v34
	v_fmac_f32_e32 v9, v16, v43
	v_mul_f32_e32 v6, v6, v9
	v_cvt_pk_bf16_f32 v6, v6, s0
	ds_write_b16 v45, v6 offset:13312
	v_mul_f32_e32 v6, 0x4b800000, v8
	v_cndmask_b32_e32 v6, v8, v6, vcc
	v_rsq_f32_e32 v6, v6
	s_nop 0
	v_mul_f32_e32 v8, 0x45800000, v6
	v_cndmask_b32_e32 v6, v6, v8, vcc
	v_mul_f32_e32 v8, v41, v40
	v_mul_f32_e32 v9, v8, v36
	v_mul_f32_e32 v6, v42, v6
	v_fma_f32 v6, v35, v6, v34
	v_mov_b32_dpp v9, v9 quad_perm:[1,0,3,2] row_mask:0xf bank_mask:0xf bound_ctrl:1
	v_fmac_f32_e32 v9, v8, v36
	s_nop 1
	v_add_f32_dpp v8, v9, v9 quad_perm:[2,3,0,1] row_mask:0xf bank_mask:0xf bound_ctrl:1
	s_nop 1
	v_add_f32_dpp v8, v8, v8 row_half_mirror row_mask:0xf bank_mask:0xf bound_ctrl:1
	s_nop 1
	v_add_f32_dpp v8, v8, v8 row_mirror row_mask:0xf bank_mask:0xf bound_ctrl:1
	s_nop 0
	v_readlane_b32 s5, v8, 16
	v_readlane_b32 s4, v8, 0
	s_nop 0
	v_mov_b32_e32 v9, s5
	v_readlane_b32 s5, v8, 48
	v_add_f32_e32 v9, s4, v9
	v_readlane_b32 s4, v8, 32
	v_mov_b32_e32 v8, s5
	s_nop 0
	v_add_f32_e32 v8, s4, v8
	v_add_f32_e32 v8, v9, v8
	v_fmac_f32_e32 v6, v8, v39
	v_mul_f32_e32 v6, v7, v6
	v_cvt_pk_bf16_f32 v6, v6, s0
	ds_write_b16 v45, v6 offset:13824
	v_mul_f32_e32 v8, v38, v37
	v_add_f32_dpp v6, v33, v33 quad_perm:[1,0,3,2] row_mask:0xf bank_mask:0xf bound_ctrl:1
	v_mul_f32_e32 v9, v8, v36
	s_nop 0
	v_add_f32_dpp v6, v6, v6 quad_perm:[2,3,0,1] row_mask:0xf bank_mask:0xf bound_ctrl:1
	v_mov_b32_dpp v9, v9 quad_perm:[1,0,3,2] row_mask:0xf bank_mask:0xf bound_ctrl:1
	v_fmac_f32_e32 v9, v8, v36
	v_add_f32_dpp v6, v6, v6 row_half_mirror row_mask:0xf bank_mask:0xf bound_ctrl:1
	s_nop 0
	v_add_f32_dpp v8, v9, v9 quad_perm:[2,3,0,1] row_mask:0xf bank_mask:0xf bound_ctrl:1
	v_add_f32_dpp v6, v6, v6 row_mirror row_mask:0xf bank_mask:0xf bound_ctrl:1
	s_nop 0
	v_readlane_b32 s13, v6, 16
	v_readlane_b32 s14, v6, 48
	v_readlane_b32 s4, v6, 0
	v_readlane_b32 s5, v6, 32
	v_mov_b32_e32 v6, s13
	v_mov_b32_e32 v7, s14
	v_pk_add_f32 v[6:7], s[4:5], v[6:7]
	v_add_f32_dpp v8, v8, v8 row_half_mirror row_mask:0xf bank_mask:0xf bound_ctrl:1
	v_add_f32_e32 v6, v6, v7
	v_fmac_f32_e32 v33, 0xbc800000, v6
	v_mul_f32_e32 v6, v33, v33
	v_add_f32_dpp v8, v8, v8 row_mirror row_mask:0xf bank_mask:0xf bound_ctrl:1
	s_nop 0
	v_mov_b32_dpp v6, v6 quad_perm:[1,0,3,2] row_mask:0xf bank_mask:0xf bound_ctrl:1
	v_fmac_f32_e32 v6, v33, v33
	s_nop 1
	v_add_f32_dpp v6, v6, v6 quad_perm:[2,3,0,1] row_mask:0xf bank_mask:0xf bound_ctrl:1
	s_nop 1
	v_add_f32_dpp v6, v6, v6 row_half_mirror row_mask:0xf bank_mask:0xf bound_ctrl:1
	s_nop 1
	v_add_f32_dpp v6, v6, v6 row_mirror row_mask:0xf bank_mask:0xf bound_ctrl:1
	s_nop 0
	v_readlane_b32 s13, v6, 16
	v_readlane_b32 s14, v6, 48
	v_readlane_b32 s4, v6, 0
	v_readlane_b32 s5, v6, 32
	v_mov_b32_e32 v6, s13
	v_mov_b32_e32 v7, s14
	v_pk_add_f32 v[6:7], s[4:5], v[6:7]
	v_readlane_b32 s5, v8, 16
	v_readlane_b32 s4, v8, 0
	v_mov_b32_e32 v11, v6
	v_mov_b32_e32 v9, s5
	v_readlane_b32 s5, v8, 48
	v_add_f32_e32 v9, s4, v9
	v_readlane_b32 s4, v8, 32
	v_mov_b32_e32 v8, s5
	s_nop 0
	v_add_f32_e32 v8, s4, v8
	v_add_f32_e32 v12, v9, v8
	s_nop 0
	v_add_f32_dpp v8, v31, v31 quad_perm:[1,0,3,2] row_mask:0xf bank_mask:0xf bound_ctrl:1
	s_nop 1
	v_add_f32_dpp v8, v8, v8 quad_perm:[2,3,0,1] row_mask:0xf bank_mask:0xf bound_ctrl:1
	s_nop 1
	v_add_f32_dpp v8, v8, v8 row_half_mirror row_mask:0xf bank_mask:0xf bound_ctrl:1
	s_nop 1
	v_add_f32_dpp v8, v8, v8 row_mirror row_mask:0xf bank_mask:0xf bound_ctrl:1
	s_nop 0
	v_readlane_b32 s13, v8, 16
	v_readlane_b32 s14, v8, 48
	v_readlane_b32 s4, v8, 0
	v_readlane_b32 s5, v8, 32
	v_mov_b32_e32 v8, s13
	v_mov_b32_e32 v9, s14
	v_pk_add_f32 v[8:9], s[4:5], v[8:9]
	s_nop 0
	v_add_f32_e32 v8, v8, v9
	v_fmac_f32_e32 v31, 0xbc800000, v8
	v_mul_f32_e32 v8, v31, v31
	s_nop 1
	v_mov_b32_dpp v8, v8 quad_perm:[1,0,3,2] row_mask:0xf bank_mask:0xf bound_ctrl:1
	v_fmac_f32_e32 v8, v31, v31
	s_nop 1
	v_add_f32_dpp v8, v8, v8 quad_perm:[2,3,0,1] row_mask:0xf bank_mask:0xf bound_ctrl:1
	s_nop 1
	v_add_f32_dpp v8, v8, v8 row_half_mirror row_mask:0xf bank_mask:0xf bound_ctrl:1
	s_nop 1
	v_add_f32_dpp v8, v8, v8 row_mirror row_mask:0xf bank_mask:0xf bound_ctrl:1
	s_nop 0
	v_readlane_b32 s13, v8, 16
	v_readlane_b32 s14, v8, 48
	v_readlane_b32 s4, v8, 0
	v_readlane_b32 s5, v8, 32
	v_mov_b32_e32 v8, s13
	v_mov_b32_e32 v9, s14
	v_pk_add_f32 v[8:9], s[4:5], v[8:9]
	s_nop 0
	v_mov_b32_e32 v10, v8
	v_mov_b32_e32 v6, v9
	v_pk_add_f32 v[6:7], v[10:11], v[6:7]
	s_nop 0
	v_pk_fma_f32 v[6:7], v[6:7], s[46:47], v[14:15] op_sel_hi:[1,0,0]
	s_nop 0
	v_mul_f32_e32 v8, 0x4b800000, v7
	v_cmp_gt_f32_e64 s[4:5], s44, v7
	v_cmp_gt_f32_e32 vcc, s44, v6
	s_nop 0
	v_cndmask_b32_e64 v7, v7, v8, s[4:5]
	v_rsq_f32_e32 v7, v7
	s_nop 0
	v_mul_f32_e32 v8, 0x45800000, v7
	v_cndmask_b32_e64 v7, v7, v8, s[4:5]
	v_mul_f32_e32 v7, v33, v7
	v_fma_f32 v7, v35, v7, v34
	v_fmac_f32_e32 v7, v12, v32
	v_mul_f32_e32 v4, v4, v7
	v_cvt_pk_bf16_f32 v4, v4, s0
	ds_write_b16 v45, v4 offset:14336
	v_mul_f32_e32 v4, 0x4b800000, v6
	v_cndmask_b32_e32 v4, v6, v4, vcc
	v_rsq_f32_e32 v4, v4
	s_nop 0
	v_mul_f32_e32 v6, 0x45800000, v4
	v_cndmask_b32_e32 v4, v4, v6, vcc
	v_mul_f32_e32 v6, v30, v29
	v_mul_f32_e32 v7, v6, v36
	v_mul_f32_e32 v4, v31, v4
	v_fma_f32 v4, v35, v4, v34
	v_mov_b32_dpp v7, v7 quad_perm:[1,0,3,2] row_mask:0xf bank_mask:0xf bound_ctrl:1
	v_fmac_f32_e32 v7, v6, v36
	s_nop 1
	v_add_f32_dpp v6, v7, v7 quad_perm:[2,3,0,1] row_mask:0xf bank_mask:0xf bound_ctrl:1
	s_nop 1
	v_add_f32_dpp v6, v6, v6 row_half_mirror row_mask:0xf bank_mask:0xf bound_ctrl:1
	s_nop 1
	v_add_f32_dpp v6, v6, v6 row_mirror row_mask:0xf bank_mask:0xf bound_ctrl:1
	s_nop 0
	v_readlane_b32 s5, v6, 16
	v_readlane_b32 s4, v6, 0
	s_nop 0
	v_mov_b32_e32 v7, s5
	v_readlane_b32 s5, v6, 48
	v_add_f32_e32 v7, s4, v7
	v_readlane_b32 s4, v6, 32
	v_mov_b32_e32 v6, s5
	s_nop 0
	v_add_f32_e32 v6, s4, v6
	v_add_f32_e32 v6, v7, v6
	v_fmac_f32_e32 v4, v6, v28
	v_mul_f32_e32 v4, v5, v4
	v_cvt_pk_bf16_f32 v4, v4, s0
	ds_write_b16 v45, v4 offset:14848
	v_mul_f32_e32 v6, v27, v26
	v_add_f32_dpp v4, v25, v25 quad_perm:[1,0,3,2] row_mask:0xf bank_mask:0xf bound_ctrl:1
	v_mul_f32_e32 v7, v6, v36
	s_nop 0
	v_add_f32_dpp v4, v4, v4 quad_perm:[2,3,0,1] row_mask:0xf bank_mask:0xf bound_ctrl:1
	v_mov_b32_dpp v7, v7 quad_perm:[1,0,3,2] row_mask:0xf bank_mask:0xf bound_ctrl:1
	v_fmac_f32_e32 v7, v6, v36
	v_add_f32_dpp v4, v4, v4 row_half_mirror row_mask:0xf bank_mask:0xf bound_ctrl:1
	s_nop 0
	v_add_f32_dpp v6, v7, v7 quad_perm:[2,3,0,1] row_mask:0xf bank_mask:0xf bound_ctrl:1
	v_add_f32_dpp v4, v4, v4 row_mirror row_mask:0xf bank_mask:0xf bound_ctrl:1
	s_nop 0
	v_readlane_b32 s13, v4, 16
	v_readlane_b32 s14, v4, 48
	v_readlane_b32 s4, v4, 0
	v_readlane_b32 s5, v4, 32
	v_mov_b32_e32 v4, s13
	v_mov_b32_e32 v5, s14
	v_pk_add_f32 v[4:5], s[4:5], v[4:5]
	v_add_f32_dpp v6, v6, v6 row_half_mirror row_mask:0xf bank_mask:0xf bound_ctrl:1
	v_add_f32_e32 v4, v4, v5
	v_fmac_f32_e32 v25, 0xbc800000, v4
	v_mul_f32_e32 v4, v25, v25
	v_add_f32_dpp v6, v6, v6 row_mirror row_mask:0xf bank_mask:0xf bound_ctrl:1
	s_nop 0
	v_mov_b32_dpp v4, v4 quad_perm:[1,0,3,2] row_mask:0xf bank_mask:0xf bound_ctrl:1
	v_fmac_f32_e32 v4, v25, v25
	s_nop 1
	v_add_f32_dpp v4, v4, v4 quad_perm:[2,3,0,1] row_mask:0xf bank_mask:0xf bound_ctrl:1
	s_nop 1
	v_add_f32_dpp v4, v4, v4 row_half_mirror row_mask:0xf bank_mask:0xf bound_ctrl:1
	s_nop 1
	v_add_f32_dpp v4, v4, v4 row_mirror row_mask:0xf bank_mask:0xf bound_ctrl:1
	s_nop 0
	v_readlane_b32 s13, v4, 16
	v_readlane_b32 s14, v4, 48
	v_readlane_b32 s4, v4, 0
	v_readlane_b32 s5, v4, 32
	v_mov_b32_e32 v4, s13
	v_mov_b32_e32 v5, s14
	v_pk_add_f32 v[4:5], s[4:5], v[4:5]
	v_readlane_b32 s5, v6, 16
	v_readlane_b32 s4, v6, 0
	v_mov_b32_e32 v9, v4
	v_mov_b32_e32 v7, s5
	v_readlane_b32 s5, v6, 48
	v_add_f32_e32 v7, s4, v7
	v_readlane_b32 s4, v6, 32
	v_mov_b32_e32 v6, s5
	s_nop 0
	v_add_f32_e32 v6, s4, v6
	v_add_f32_e32 v10, v7, v6
	s_nop 0
	v_add_f32_dpp v6, v23, v23 quad_perm:[1,0,3,2] row_mask:0xf bank_mask:0xf bound_ctrl:1
	s_nop 1
	v_add_f32_dpp v6, v6, v6 quad_perm:[2,3,0,1] row_mask:0xf bank_mask:0xf bound_ctrl:1
	s_nop 1
	v_add_f32_dpp v6, v6, v6 row_half_mirror row_mask:0xf bank_mask:0xf bound_ctrl:1
	s_nop 1
	v_add_f32_dpp v6, v6, v6 row_mirror row_mask:0xf bank_mask:0xf bound_ctrl:1
	s_nop 0
	v_readlane_b32 s13, v6, 16
	v_readlane_b32 s14, v6, 48
	v_readlane_b32 s4, v6, 0
	v_readlane_b32 s5, v6, 32
	v_mov_b32_e32 v6, s13
	v_mov_b32_e32 v7, s14
	v_pk_add_f32 v[6:7], s[4:5], v[6:7]
	s_nop 0
	v_add_f32_e32 v6, v6, v7
	v_fmac_f32_e32 v23, 0xbc800000, v6
	v_mul_f32_e32 v6, v23, v23
	s_nop 1
	v_mov_b32_dpp v6, v6 quad_perm:[1,0,3,2] row_mask:0xf bank_mask:0xf bound_ctrl:1
	v_fmac_f32_e32 v6, v23, v23
	s_nop 1
	v_add_f32_dpp v6, v6, v6 quad_perm:[2,3,0,1] row_mask:0xf bank_mask:0xf bound_ctrl:1
	s_nop 1
	v_add_f32_dpp v6, v6, v6 row_half_mirror row_mask:0xf bank_mask:0xf bound_ctrl:1
	s_nop 1
	v_add_f32_dpp v6, v6, v6 row_mirror row_mask:0xf bank_mask:0xf bound_ctrl:1
	s_nop 0
	v_readlane_b32 s13, v6, 16
	v_readlane_b32 s14, v6, 48
	v_readlane_b32 s4, v6, 0
	v_readlane_b32 s5, v6, 32
	v_mov_b32_e32 v6, s13
	v_mov_b32_e32 v7, s14
	v_pk_add_f32 v[6:7], s[4:5], v[6:7]
	s_nop 0
	v_mov_b32_e32 v8, v6
	v_mov_b32_e32 v4, v7
	v_pk_add_f32 v[4:5], v[8:9], v[4:5]
	s_nop 0
	v_pk_fma_f32 v[4:5], v[4:5], s[46:47], v[14:15] op_sel_hi:[1,0,0]
	s_nop 0
	v_mul_f32_e32 v6, 0x4b800000, v5
	v_cmp_gt_f32_e64 s[4:5], s44, v5
	v_cmp_gt_f32_e32 vcc, s44, v4
	s_nop 0
	v_cndmask_b32_e64 v5, v5, v6, s[4:5]
	v_rsq_f32_e32 v5, v5
	s_nop 0
	v_mul_f32_e32 v6, 0x45800000, v5
	v_cndmask_b32_e64 v5, v5, v6, s[4:5]
	v_mul_f32_e32 v5, v25, v5
	v_fma_f32 v5, v35, v5, v34
	v_fmac_f32_e32 v5, v10, v24
	v_mul_f32_e32 v2, v2, v5
	v_cvt_pk_bf16_f32 v2, v2, s0
	ds_write_b16 v45, v2 offset:15360
	v_mul_f32_e32 v2, 0x4b800000, v4
	v_cndmask_b32_e32 v2, v4, v2, vcc
	v_rsq_f32_e32 v2, v2
	s_nop 0
	v_mul_f32_e32 v4, 0x45800000, v2
	v_cndmask_b32_e32 v2, v2, v4, vcc
	v_mul_f32_e32 v2, v23, v2
	v_fmac_f32_e32 v34, v35, v2
	v_mul_f32_e32 v2, v22, v21
	v_mul_f32_e32 v4, v2, v36
	s_nop 1
	v_mov_b32_dpp v4, v4 quad_perm:[1,0,3,2] row_mask:0xf bank_mask:0xf bound_ctrl:1
	v_fmac_f32_e32 v4, v2, v36
	s_nop 1
	v_add_f32_dpp v2, v4, v4 quad_perm:[2,3,0,1] row_mask:0xf bank_mask:0xf bound_ctrl:1
	s_nop 1
	v_add_f32_dpp v2, v2, v2 row_half_mirror row_mask:0xf bank_mask:0xf bound_ctrl:1
	s_nop 1
	v_add_f32_dpp v2, v2, v2 row_mirror row_mask:0xf bank_mask:0xf bound_ctrl:1
	s_nop 0
	v_readlane_b32 s5, v2, 16
	v_readlane_b32 s4, v2, 0
	s_nop 0
	v_mov_b32_e32 v4, s5
	v_readlane_b32 s5, v2, 48
	v_add_f32_e32 v4, s4, v4
	v_readlane_b32 s4, v2, 32
	v_mov_b32_e32 v2, s5
	s_nop 0
	v_add_f32_e32 v2, s4, v2
	v_add_f32_e32 v2, v4, v2
	v_fmac_f32_e32 v34, v2, v1
	v_mul_f32_e32 v1, v3, v34
	v_cvt_pk_bf16_f32 v1, v1, s0
	ds_write_b16 v45, v1 offset:15872
	v_lshlrev_b32_e32 v1, 4, v0
	v_and_b32_e32 v176, 0x1f0, v1
	v_add_u32_e32 v6, 16, v176
	v_ashrrev_i32_e32 v4, 5, v0
	v_lshl_add_u32 v0, v4, 9, v6
	s_waitcnt lgkmcnt(0)
	s_barrier
	ds_read_b128 v[0:3], v0 offset:8192
	v_add_u32_e32 v4, s12, v4
	v_ashrrev_i32_e32 v5, 31, v4
	v_lshlrev_b64 v[4:5], 9, v[4:5]
	v_lshl_add_u64 v[4:5], s[28:29], 0, v[4:5]
	v_lshl_add_u64 v[4:5], v[4:5], 0, v[176:177]
	s_waitcnt lgkmcnt(0)
	global_store_dwordx4 v[4:5], v[0:3], off
	v_ashrrev_i32_e32 v4, 5, v20
	s_nop 0
	v_lshl_add_u32 v0, v4, 9, v6
	ds_read_b128 v[0:3], v0 offset:8192
	v_add_u32_e32 v4, s12, v4
	v_ashrrev_i32_e32 v5, 31, v4
	v_lshlrev_b64 v[4:5], 9, v[4:5]
	v_lshl_add_u64 v[4:5], s[28:29], 0, v[4:5]
	v_lshl_add_u64 v[4:5], v[4:5], 0, v[176:177]
	s_waitcnt lgkmcnt(0)
	global_store_dwordx4 v[4:5], v[0:3], off
	s_barrier
	s_branch .LBB0_584
